# GEMM K-loops: pair serpentine with runs of four sharing the second MFMA operand (both 16-MFMA blocks merged)
# speedup vs baseline: 1.0022x; 1.0022x over previous
.LBB0_383:
	s_ashr_i32 s67, s66, 31
	s_lshl_b64 s[26:27], s[66:67], 19
	s_add_u32 s26, s40, s26
	s_addc_u32 s27, s41, s27
	s_and_b64 s[34:35], s[8:9], exec
	s_cselect_b32 s34, s27, s5
	s_cselect_b32 s35, s26, s4
	s_ashr_i32 s29, s28, 31
	s_lshl_b64 s[38:39], s[28:29], 19
	s_add_u32 s62, s10, s38
	s_addc_u32 s63, s11, s39
	s_and_b64 s[38:39], s[8:9], exec
	s_cselect_b32 s29, s63, s83
	s_cselect_b32 s38, s62, s82
	s_add_u32 s39, s82, 0x100
	s_addc_u32 s67, s83, 0
	s_mov_b32 s94, -2
	s_mov_b64 vcc, 0
	v_lshl_add_u64 v[132:133], s[4:5], 0, v[168:169]
	ds_read_b128 v[134:137], v199
	ds_read_b128 v[138:141], v200
	ds_read_b128 v[142:145], v201
	ds_read_b128 v[146:149], v202
	ds_read_b128 v[150:153], v203
	ds_read_b128 v[174:177], v204
	ds_read_b128 v[178:181], v205
	ds_read_b128 v[182:185], v206
	s_add_u32 s24, s4, vcc_lo
	s_addc_u32 s25, s5, vcc_hi
	s_add_u32 s24, s24, 0x100
	s_addc_u32 s25, s25, 0
	s_add_u32 s82, s39, vcc_lo
	s_addc_u32 s83, s67, vcc_hi
	s_cmpk_eq_i32 vcc_lo, 0x700
	s_cselect_b32 s87, s29, s83
	s_cselect_b32 s86, s38, s82
	s_cselect_b32 s83, s34, s25
	s_cselect_b32 s82, s35, s24
	v_lshl_add_u64 v[154:155], v[132:133], 0, vcc
	v_lshl_add_u64 v[250:251], v[154:155], 0, s[48:49]
	s_add_i32 m0, s79, 0x8000
	s_mov_b64 s[24:25], 0x20080
	ds_read_b128 v[218:221], v207
	ds_read_b128 v[222:225], v207 offset:2048
	ds_read_b128 v[226:229], v208
	ds_read_b128 v[230:233], v208 offset:2048
	ds_read_b128 v[234:237], v207 offset:4096
	ds_read_b128 v[238:241], v207 offset:6144
	ds_read_b128 v[242:245], v208 offset:4096
	ds_read_b128 v[246:249], v208 offset:6144
	global_load_lds_dwordx4 v[250:251], off
	v_lshl_add_u64 v[250:251], v[154:155], 0, s[24:25]
	s_add_i32 m0, s79, 0xa000
	s_mov_b64 s[24:25], 0x60080
	global_load_lds_dwordx4 v[250:251], off
	v_lshl_add_u64 v[250:251], v[154:155], 0, s[50:51]
	s_add_i32 m0, s79, 0xc000
	v_lshl_add_u64 v[154:155], v[154:155], 0, s[24:25]
	global_load_lds_dwordx4 v[250:251], off
	s_add_i32 m0, s79, 0xe000
	s_nop 0
	global_load_lds_dwordx4 v[154:155], off
	s_waitcnt lgkmcnt(0)
	s_barrier
	v_mfma_f32_16x16x32_bf16 v[128:131], v[134:137], v[218:221], 0
	v_mfma_f32_16x16x32_bf16 v[128:131], v[138:141], v[226:229], v[128:131]
	v_mfma_f32_16x16x32_bf16 v[124:127], v[142:145], v[218:221], 0
	v_mfma_f32_16x16x32_bf16 v[124:127], v[146:149], v[226:229], v[124:127]
	v_mfma_f32_16x16x32_bf16 v[120:123], v[150:153], v[218:221], 0
	v_mfma_f32_16x16x32_bf16 v[120:123], v[174:177], v[226:229], v[120:123]
	v_mfma_f32_16x16x32_bf16 v[116:119], v[178:181], v[218:221], 0
	v_mfma_f32_16x16x32_bf16 v[116:119], v[182:185], v[226:229], v[116:119]
	v_mfma_f32_16x16x32_bf16 v[100:103], v[178:181], v[222:225], 0
	v_mfma_f32_16x16x32_bf16 v[100:103], v[182:185], v[230:233], v[100:103]
	v_mfma_f32_16x16x32_bf16 v[104:107], v[150:153], v[222:225], 0
	v_mfma_f32_16x16x32_bf16 v[104:107], v[174:177], v[230:233], v[104:107]
	v_mfma_f32_16x16x32_bf16 v[108:111], v[142:145], v[222:225], 0
	v_mfma_f32_16x16x32_bf16 v[108:111], v[146:149], v[230:233], v[108:111]
	v_mfma_f32_16x16x32_bf16 v[112:115], v[134:137], v[222:225], 0
	v_mfma_f32_16x16x32_bf16 v[112:115], v[138:141], v[230:233], v[112:115]
	v_mfma_f32_16x16x32_bf16 v[96:99], v[134:137], v[234:237], 0
	v_mfma_f32_16x16x32_bf16 v[96:99], v[138:141], v[242:245], v[96:99]
	v_mfma_f32_16x16x32_bf16 v[92:95], v[142:145], v[234:237], 0
	v_mfma_f32_16x16x32_bf16 v[92:95], v[146:149], v[242:245], v[92:95]
	v_mfma_f32_16x16x32_bf16 v[88:91], v[150:153], v[234:237], 0
	v_mfma_f32_16x16x32_bf16 v[88:91], v[174:177], v[242:245], v[88:91]
	v_mfma_f32_16x16x32_bf16 v[84:87], v[178:181], v[234:237], 0
	v_mfma_f32_16x16x32_bf16 v[84:87], v[182:185], v[242:245], v[84:87]
	v_mfma_f32_16x16x32_bf16 v[68:71], v[178:181], v[238:241], 0
	v_mfma_f32_16x16x32_bf16 v[68:71], v[182:185], v[246:249], v[68:71]
	v_mfma_f32_16x16x32_bf16 v[72:75], v[150:153], v[238:241], 0
	v_mfma_f32_16x16x32_bf16 v[72:75], v[174:177], v[246:249], v[72:75]
	v_mfma_f32_16x16x32_bf16 v[76:79], v[142:145], v[238:241], 0
	v_mfma_f32_16x16x32_bf16 v[76:79], v[146:149], v[246:249], v[76:79]
	v_mfma_f32_16x16x32_bf16 v[80:83], v[134:137], v[238:241], 0
	v_mfma_f32_16x16x32_bf16 v[80:83], v[138:141], v[246:249], v[80:83]
	s_barrier
	s_add_i32 s24, s1, s77
	v_lshl_add_u64 v[154:155], s[86:87], 0, v[158:159]
	s_mov_b32 m0, s24
	ds_read_b128 v[218:221], v207 offset:16384
	ds_read_b128 v[222:225], v207 offset:18432
	ds_read_b128 v[226:229], v208 offset:16384
	ds_read_b128 v[230:233], v208 offset:18432
	ds_read_b128 v[234:237], v207 offset:20480
	ds_read_b128 v[238:241], v207 offset:22528
	ds_read_b128 v[242:245], v208 offset:20480
	ds_read_b128 v[246:249], v208 offset:22528
	global_load_lds_dwordx4 v[154:155], off
	v_lshl_add_u64 v[250:251], v[154:155], 0, s[14:15]
	s_add_i32 m0, s24, 0x2000
	s_add_i32 s24, s12, s77
	global_load_lds_dwordx4 v[250:251], off
	v_lshl_add_u64 v[250:251], v[154:155], 0, s[16:17]
	s_mov_b32 m0, s24
	s_nop 0
	global_load_lds_dwordx4 v[250:251], off
	v_lshl_add_u64 v[250:251], v[154:155], 0, s[18:19]
	s_add_i32 m0, s24, 0x2000
	s_nop 0
	global_load_lds_dwordx4 v[250:251], off
	s_waitcnt vmcnt(4)
	s_waitcnt lgkmcnt(0)
	s_barrier
	v_mfma_f32_16x16x32_bf16 v[64:67], v[134:137], v[218:221], 0
	v_mfma_f32_16x16x32_bf16 v[64:67], v[138:141], v[226:229], v[64:67]
	v_mfma_f32_16x16x32_bf16 v[60:63], v[142:145], v[218:221], 0
	v_mfma_f32_16x16x32_bf16 v[60:63], v[146:149], v[226:229], v[60:63]
	v_mfma_f32_16x16x32_bf16 v[56:59], v[150:153], v[218:221], 0
	v_mfma_f32_16x16x32_bf16 v[56:59], v[174:177], v[226:229], v[56:59]
	v_mfma_f32_16x16x32_bf16 v[52:55], v[178:181], v[218:221], 0
	v_mfma_f32_16x16x32_bf16 v[52:55], v[182:185], v[226:229], v[52:55]
	v_mfma_f32_16x16x32_bf16 v[36:39], v[178:181], v[222:225], 0
	v_mfma_f32_16x16x32_bf16 v[36:39], v[182:185], v[230:233], v[36:39]
	v_mfma_f32_16x16x32_bf16 v[40:43], v[150:153], v[222:225], 0
	v_mfma_f32_16x16x32_bf16 v[40:43], v[174:177], v[230:233], v[40:43]
	v_mfma_f32_16x16x32_bf16 v[44:47], v[142:145], v[222:225], 0
	v_mfma_f32_16x16x32_bf16 v[44:47], v[146:149], v[230:233], v[44:47]
	v_mfma_f32_16x16x32_bf16 v[48:51], v[134:137], v[222:225], 0
	v_mfma_f32_16x16x32_bf16 v[48:51], v[138:141], v[230:233], v[48:51]
	v_mfma_f32_16x16x32_bf16 v[32:35], v[134:137], v[234:237], 0
	v_mfma_f32_16x16x32_bf16 v[32:35], v[138:141], v[242:245], v[32:35]
	v_mfma_f32_16x16x32_bf16 v[28:31], v[142:145], v[234:237], 0
	v_mfma_f32_16x16x32_bf16 v[28:31], v[146:149], v[242:245], v[28:31]
	v_mfma_f32_16x16x32_bf16 v[24:27], v[150:153], v[234:237], 0
	v_mfma_f32_16x16x32_bf16 v[24:27], v[174:177], v[242:245], v[24:27]
	v_mfma_f32_16x16x32_bf16 v[20:23], v[178:181], v[234:237], 0
	v_mfma_f32_16x16x32_bf16 v[20:23], v[182:185], v[242:245], v[20:23]
	v_mfma_f32_16x16x32_bf16 v[4:7], v[178:181], v[238:241], 0
	v_mfma_f32_16x16x32_bf16 v[4:7], v[182:185], v[246:249], v[4:7]
	v_mfma_f32_16x16x32_bf16 v[8:11], v[150:153], v[238:241], 0
	v_mfma_f32_16x16x32_bf16 v[8:11], v[174:177], v[246:249], v[8:11]
	v_mfma_f32_16x16x32_bf16 v[12:15], v[142:145], v[238:241], 0
	v_mfma_f32_16x16x32_bf16 v[12:15], v[146:149], v[246:249], v[12:15]
	v_mfma_f32_16x16x32_bf16 v[16:19], v[134:137], v[238:241], 0
	v_mfma_f32_16x16x32_bf16 v[16:19], v[138:141], v[246:249], v[16:19]
	s_barrier
	ds_read_b128 v[134:137], v213
	ds_read_b128 v[138:141], v214
	ds_read_b128 v[142:145], v209
	ds_read_b128 v[146:149], v210
	ds_read_b128 v[150:153], v215
	ds_read_b128 v[174:177], v216
	ds_read_b128 v[178:181], v211
	ds_read_b128 v[182:185], v212
	s_mov_b32 m0, s79
	v_lshl_add_u64 v[250:251], s[82:83], 0, v[0:1]
	ds_read_b128 v[218:221], v207 offset:32768
	ds_read_b128 v[222:225], v207 offset:34816
	ds_read_b128 v[226:229], v208 offset:32768
	ds_read_b128 v[230:233], v208 offset:34816
	ds_read_b128 v[234:237], v207 offset:36864
	ds_read_b128 v[238:241], v207 offset:38912
	ds_read_b128 v[242:245], v208 offset:36864
	ds_read_b128 v[246:249], v208 offset:38912
	global_load_lds_dwordx4 v[250:251], off
	v_lshl_add_u64 v[252:253], v[250:251], 0, s[20:21]
	s_mov_b32 m0, s81
	s_nop 0
	global_load_lds_dwordx4 v[252:253], off
	v_lshl_add_u64 v[252:253], v[250:251], 0, s[14:15]
	s_mov_b32 m0, s97
	v_lshl_add_u64 v[250:251], v[250:251], 0, s[22:23]
	global_load_lds_dwordx4 v[252:253], off
	s_mov_b32 m0, s64
	s_nop 0
	global_load_lds_dwordx4 v[250:251], off
	s_waitcnt vmcnt(8)
	s_waitcnt lgkmcnt(0)
	s_barrier
	v_mfma_f32_16x16x32_bf16 v[128:131], v[134:137], v[218:221], v[128:131]
	v_mfma_f32_16x16x32_bf16 v[128:131], v[138:141], v[226:229], v[128:131]
	v_mfma_f32_16x16x32_bf16 v[124:127], v[146:149], v[226:229], v[124:127]
	v_mfma_f32_16x16x32_bf16 v[124:127], v[142:145], v[218:221], v[124:127]
	v_mfma_f32_16x16x32_bf16 v[120:123], v[150:153], v[218:221], v[120:123]
	v_mfma_f32_16x16x32_bf16 v[120:123], v[174:177], v[226:229], v[120:123]
	v_mfma_f32_16x16x32_bf16 v[116:119], v[182:185], v[226:229], v[116:119]
	v_mfma_f32_16x16x32_bf16 v[116:119], v[178:181], v[218:221], v[116:119]
	v_mfma_f32_16x16x32_bf16 v[100:103], v[178:181], v[222:225], v[100:103]
	v_mfma_f32_16x16x32_bf16 v[100:103], v[182:185], v[230:233], v[100:103]
	v_mfma_f32_16x16x32_bf16 v[104:107], v[174:177], v[230:233], v[104:107]
	v_mfma_f32_16x16x32_bf16 v[104:107], v[150:153], v[222:225], v[104:107]
	v_mfma_f32_16x16x32_bf16 v[108:111], v[142:145], v[222:225], v[108:111]
	v_mfma_f32_16x16x32_bf16 v[108:111], v[146:149], v[230:233], v[108:111]
	v_mfma_f32_16x16x32_bf16 v[112:115], v[138:141], v[230:233], v[112:115]
	v_mfma_f32_16x16x32_bf16 v[112:115], v[134:137], v[222:225], v[112:115]
	v_mfma_f32_16x16x32_bf16 v[96:99], v[134:137], v[234:237], v[96:99]
	v_mfma_f32_16x16x32_bf16 v[96:99], v[138:141], v[242:245], v[96:99]
	v_mfma_f32_16x16x32_bf16 v[92:95], v[146:149], v[242:245], v[92:95]
	v_mfma_f32_16x16x32_bf16 v[92:95], v[142:145], v[234:237], v[92:95]
	v_mfma_f32_16x16x32_bf16 v[88:91], v[150:153], v[234:237], v[88:91]
	v_mfma_f32_16x16x32_bf16 v[88:91], v[174:177], v[242:245], v[88:91]
	v_mfma_f32_16x16x32_bf16 v[84:87], v[182:185], v[242:245], v[84:87]
	v_mfma_f32_16x16x32_bf16 v[84:87], v[178:181], v[234:237], v[84:87]
	v_mfma_f32_16x16x32_bf16 v[68:71], v[178:181], v[238:241], v[68:71]
	v_mfma_f32_16x16x32_bf16 v[68:71], v[182:185], v[246:249], v[68:71]
	v_mfma_f32_16x16x32_bf16 v[72:75], v[174:177], v[246:249], v[72:75]
	v_mfma_f32_16x16x32_bf16 v[72:75], v[150:153], v[238:241], v[72:75]
	v_mfma_f32_16x16x32_bf16 v[76:79], v[142:145], v[238:241], v[76:79]
	v_mfma_f32_16x16x32_bf16 v[76:79], v[146:149], v[246:249], v[76:79]
	v_mfma_f32_16x16x32_bf16 v[80:83], v[138:141], v[246:249], v[80:83]
	v_mfma_f32_16x16x32_bf16 v[80:83], v[134:137], v[238:241], v[80:83]
	s_barrier
	s_add_i32 s24, s70, s77
	v_lshl_add_u64 v[250:251], v[154:155], 0, s[48:49]
	s_mov_b32 m0, s24
	ds_read_b128 v[218:221], v207 offset:49152
	ds_read_b128 v[222:225], v207 offset:51200
	ds_read_b128 v[226:229], v208 offset:49152
	ds_read_b128 v[230:233], v208 offset:51200
	ds_read_b128 v[234:237], v207 offset:53248
	ds_read_b128 v[238:241], v207 offset:55296
	ds_read_b128 v[242:245], v208 offset:53248
	ds_read_b128 v[246:249], v208 offset:55296
	global_load_lds_dwordx4 v[250:251], off
	v_lshl_add_u64 v[250:251], v[154:155], 0, s[50:51]
	s_add_i32 m0, s24, 0x2000
	s_add_i32 s24, s71, s77
	global_load_lds_dwordx4 v[250:251], off
	v_lshl_add_u64 v[250:251], v[154:155], 0, s[52:53]
	s_mov_b32 m0, s24
	v_lshl_add_u64 v[154:155], v[154:155], 0, s[54:55]
	global_load_lds_dwordx4 v[250:251], off
	s_add_i32 m0, s24, 0x2000
	s_nop 0
	global_load_lds_dwordx4 v[154:155], off
	s_waitcnt vmcnt(4)
	s_waitcnt lgkmcnt(0)
	s_barrier
	v_mfma_f32_16x16x32_bf16 v[64:67], v[134:137], v[218:221], v[64:67]
	v_mfma_f32_16x16x32_bf16 v[64:67], v[138:141], v[226:229], v[64:67]
	v_mfma_f32_16x16x32_bf16 v[60:63], v[146:149], v[226:229], v[60:63]
	v_mfma_f32_16x16x32_bf16 v[60:63], v[142:145], v[218:221], v[60:63]
	v_mfma_f32_16x16x32_bf16 v[56:59], v[150:153], v[218:221], v[56:59]
	v_mfma_f32_16x16x32_bf16 v[56:59], v[174:177], v[226:229], v[56:59]
	v_mfma_f32_16x16x32_bf16 v[52:55], v[182:185], v[226:229], v[52:55]
	v_mfma_f32_16x16x32_bf16 v[52:55], v[178:181], v[218:221], v[52:55]
	v_mfma_f32_16x16x32_bf16 v[36:39], v[178:181], v[222:225], v[36:39]
	v_mfma_f32_16x16x32_bf16 v[36:39], v[182:185], v[230:233], v[36:39]
	v_mfma_f32_16x16x32_bf16 v[40:43], v[174:177], v[230:233], v[40:43]
	v_mfma_f32_16x16x32_bf16 v[40:43], v[150:153], v[222:225], v[40:43]
	v_mfma_f32_16x16x32_bf16 v[44:47], v[142:145], v[222:225], v[44:47]
	v_mfma_f32_16x16x32_bf16 v[44:47], v[146:149], v[230:233], v[44:47]
	v_mfma_f32_16x16x32_bf16 v[48:51], v[138:141], v[230:233], v[48:51]
	v_mfma_f32_16x16x32_bf16 v[48:51], v[134:137], v[222:225], v[48:51]
	v_mfma_f32_16x16x32_bf16 v[32:35], v[134:137], v[234:237], v[32:35]
	v_mfma_f32_16x16x32_bf16 v[32:35], v[138:141], v[242:245], v[32:35]
	v_mfma_f32_16x16x32_bf16 v[28:31], v[146:149], v[242:245], v[28:31]
	v_mfma_f32_16x16x32_bf16 v[28:31], v[142:145], v[234:237], v[28:31]
	v_mfma_f32_16x16x32_bf16 v[24:27], v[150:153], v[234:237], v[24:27]
	v_mfma_f32_16x16x32_bf16 v[24:27], v[174:177], v[242:245], v[24:27]
	v_mfma_f32_16x16x32_bf16 v[20:23], v[182:185], v[242:245], v[20:23]
	v_mfma_f32_16x16x32_bf16 v[20:23], v[178:181], v[234:237], v[20:23]
	v_mfma_f32_16x16x32_bf16 v[4:7], v[178:181], v[238:241], v[4:7]
	v_mfma_f32_16x16x32_bf16 v[4:7], v[182:185], v[246:249], v[4:7]
	v_mfma_f32_16x16x32_bf16 v[8:11], v[174:177], v[246:249], v[8:11]
	v_mfma_f32_16x16x32_bf16 v[8:11], v[150:153], v[238:241], v[8:11]
	v_mfma_f32_16x16x32_bf16 v[12:15], v[142:145], v[238:241], v[12:15]
	v_mfma_f32_16x16x32_bf16 v[12:15], v[146:149], v[246:249], v[12:15]
	v_mfma_f32_16x16x32_bf16 v[16:19], v[138:141], v[246:249], v[16:19]
	v_mfma_f32_16x16x32_bf16 v[16:19], v[134:137], v[238:241], v[16:19]
	s_barrier
	s_add_i32 s94, s94, 2
	s_add_u32 vcc_lo, vcc_lo, 0x100
	s_addc_u32 vcc_hi, vcc_hi, 0
	s_cmp_gt_u32 s94, 13
.LBB0_384:
	ds_read_b128 v[134:137], v199
	ds_read_b128 v[138:141], v200
	ds_read_b128 v[142:145], v201
	ds_read_b128 v[146:149], v202
	ds_read_b128 v[150:153], v203
	ds_read_b128 v[174:177], v204
	ds_read_b128 v[178:181], v205
	ds_read_b128 v[182:185], v206
	s_add_u32 s24, s4, vcc_lo
	s_addc_u32 s25, s5, vcc_hi
	s_add_u32 s24, s24, 0x100
	s_addc_u32 s25, s25, 0
	s_add_u32 s82, s39, vcc_lo
	s_addc_u32 s83, s67, vcc_hi
	s_cmpk_eq_i32 vcc_lo, 0x700
	s_cselect_b32 s87, s29, s83
	s_cselect_b32 s86, s38, s82
	s_cselect_b32 s83, s34, s25
	s_cselect_b32 s82, s35, s24
	v_lshl_add_u64 v[154:155], v[132:133], 0, vcc
	v_lshl_add_u64 v[250:251], v[154:155], 0, s[48:49]
	s_add_i32 m0, s79, 0x8000
	s_mov_b64 s[24:25], 0x20080
	ds_read_b128 v[218:221], v207
	ds_read_b128 v[222:225], v207 offset:2048
	ds_read_b128 v[226:229], v208
	ds_read_b128 v[230:233], v208 offset:2048
	ds_read_b128 v[234:237], v207 offset:4096
	ds_read_b128 v[238:241], v207 offset:6144
	ds_read_b128 v[242:245], v208 offset:4096
	ds_read_b128 v[246:249], v208 offset:6144
	global_load_lds_dwordx4 v[250:251], off
	v_lshl_add_u64 v[250:251], v[154:155], 0, s[24:25]
	s_add_i32 m0, s79, 0xa000
	s_mov_b64 s[24:25], 0x60080
	global_load_lds_dwordx4 v[250:251], off
	v_lshl_add_u64 v[250:251], v[154:155], 0, s[50:51]
	s_add_i32 m0, s79, 0xc000
	v_lshl_add_u64 v[154:155], v[154:155], 0, s[24:25]
	global_load_lds_dwordx4 v[250:251], off
	s_add_i32 m0, s79, 0xe000
	s_nop 0
	global_load_lds_dwordx4 v[154:155], off
	s_waitcnt vmcnt(8)
	s_waitcnt lgkmcnt(0)
	s_barrier
	v_mfma_f32_16x16x32_bf16 v[128:131], v[134:137], v[218:221], v[128:131]
	v_mfma_f32_16x16x32_bf16 v[128:131], v[138:141], v[226:229], v[128:131]
	v_mfma_f32_16x16x32_bf16 v[124:127], v[146:149], v[226:229], v[124:127]
	v_mfma_f32_16x16x32_bf16 v[124:127], v[142:145], v[218:221], v[124:127]
	v_mfma_f32_16x16x32_bf16 v[120:123], v[150:153], v[218:221], v[120:123]
	v_mfma_f32_16x16x32_bf16 v[120:123], v[174:177], v[226:229], v[120:123]
	v_mfma_f32_16x16x32_bf16 v[116:119], v[182:185], v[226:229], v[116:119]
	v_mfma_f32_16x16x32_bf16 v[116:119], v[178:181], v[218:221], v[116:119]
	v_mfma_f32_16x16x32_bf16 v[100:103], v[178:181], v[222:225], v[100:103]
	v_mfma_f32_16x16x32_bf16 v[100:103], v[182:185], v[230:233], v[100:103]
	v_mfma_f32_16x16x32_bf16 v[104:107], v[174:177], v[230:233], v[104:107]
	v_mfma_f32_16x16x32_bf16 v[104:107], v[150:153], v[222:225], v[104:107]
	v_mfma_f32_16x16x32_bf16 v[108:111], v[142:145], v[222:225], v[108:111]
	v_mfma_f32_16x16x32_bf16 v[108:111], v[146:149], v[230:233], v[108:111]
	v_mfma_f32_16x16x32_bf16 v[112:115], v[138:141], v[230:233], v[112:115]
	v_mfma_f32_16x16x32_bf16 v[112:115], v[134:137], v[222:225], v[112:115]
	v_mfma_f32_16x16x32_bf16 v[96:99], v[134:137], v[234:237], v[96:99]
	v_mfma_f32_16x16x32_bf16 v[96:99], v[138:141], v[242:245], v[96:99]
	v_mfma_f32_16x16x32_bf16 v[92:95], v[146:149], v[242:245], v[92:95]
	v_mfma_f32_16x16x32_bf16 v[92:95], v[142:145], v[234:237], v[92:95]
	v_mfma_f32_16x16x32_bf16 v[88:91], v[150:153], v[234:237], v[88:91]
	v_mfma_f32_16x16x32_bf16 v[88:91], v[174:177], v[242:245], v[88:91]
	v_mfma_f32_16x16x32_bf16 v[84:87], v[182:185], v[242:245], v[84:87]
	v_mfma_f32_16x16x32_bf16 v[84:87], v[178:181], v[234:237], v[84:87]
	v_mfma_f32_16x16x32_bf16 v[68:71], v[178:181], v[238:241], v[68:71]
	v_mfma_f32_16x16x32_bf16 v[68:71], v[182:185], v[246:249], v[68:71]
	v_mfma_f32_16x16x32_bf16 v[72:75], v[174:177], v[246:249], v[72:75]
	v_mfma_f32_16x16x32_bf16 v[72:75], v[150:153], v[238:241], v[72:75]
	v_mfma_f32_16x16x32_bf16 v[76:79], v[142:145], v[238:241], v[76:79]
	v_mfma_f32_16x16x32_bf16 v[76:79], v[146:149], v[246:249], v[76:79]
	v_mfma_f32_16x16x32_bf16 v[80:83], v[138:141], v[246:249], v[80:83]
	v_mfma_f32_16x16x32_bf16 v[80:83], v[134:137], v[238:241], v[80:83]
	s_barrier
	s_add_i32 s24, s1, s77
	v_lshl_add_u64 v[154:155], s[86:87], 0, v[158:159]
	s_mov_b32 m0, s24
	ds_read_b128 v[218:221], v207 offset:16384
	ds_read_b128 v[222:225], v207 offset:18432
	ds_read_b128 v[226:229], v208 offset:16384
	ds_read_b128 v[230:233], v208 offset:18432
	ds_read_b128 v[234:237], v207 offset:20480
	ds_read_b128 v[238:241], v207 offset:22528
	ds_read_b128 v[242:245], v208 offset:20480
	ds_read_b128 v[246:249], v208 offset:22528
	global_load_lds_dwordx4 v[154:155], off
	v_lshl_add_u64 v[250:251], v[154:155], 0, s[14:15]
	s_add_i32 m0, s24, 0x2000
	s_add_i32 s24, s12, s77
	global_load_lds_dwordx4 v[250:251], off
	v_lshl_add_u64 v[250:251], v[154:155], 0, s[16:17]
	s_mov_b32 m0, s24
	s_nop 0
	global_load_lds_dwordx4 v[250:251], off
	v_lshl_add_u64 v[250:251], v[154:155], 0, s[18:19]
	s_add_i32 m0, s24, 0x2000
	s_nop 0
	global_load_lds_dwordx4 v[250:251], off
	s_waitcnt vmcnt(4)
	s_waitcnt lgkmcnt(0)
	s_barrier
	v_mfma_f32_16x16x32_bf16 v[64:67], v[134:137], v[218:221], v[64:67]
	v_mfma_f32_16x16x32_bf16 v[64:67], v[138:141], v[226:229], v[64:67]
	v_mfma_f32_16x16x32_bf16 v[60:63], v[146:149], v[226:229], v[60:63]
	v_mfma_f32_16x16x32_bf16 v[60:63], v[142:145], v[218:221], v[60:63]
	v_mfma_f32_16x16x32_bf16 v[56:59], v[150:153], v[218:221], v[56:59]
	v_mfma_f32_16x16x32_bf16 v[56:59], v[174:177], v[226:229], v[56:59]
	v_mfma_f32_16x16x32_bf16 v[52:55], v[182:185], v[226:229], v[52:55]
	v_mfma_f32_16x16x32_bf16 v[52:55], v[178:181], v[218:221], v[52:55]
	v_mfma_f32_16x16x32_bf16 v[36:39], v[178:181], v[222:225], v[36:39]
	v_mfma_f32_16x16x32_bf16 v[36:39], v[182:185], v[230:233], v[36:39]
	v_mfma_f32_16x16x32_bf16 v[40:43], v[174:177], v[230:233], v[40:43]
	v_mfma_f32_16x16x32_bf16 v[40:43], v[150:153], v[222:225], v[40:43]
	v_mfma_f32_16x16x32_bf16 v[44:47], v[142:145], v[222:225], v[44:47]
	v_mfma_f32_16x16x32_bf16 v[44:47], v[146:149], v[230:233], v[44:47]
	v_mfma_f32_16x16x32_bf16 v[48:51], v[138:141], v[230:233], v[48:51]
	v_mfma_f32_16x16x32_bf16 v[48:51], v[134:137], v[222:225], v[48:51]
	v_mfma_f32_16x16x32_bf16 v[32:35], v[134:137], v[234:237], v[32:35]
	v_mfma_f32_16x16x32_bf16 v[32:35], v[138:141], v[242:245], v[32:35]
	v_mfma_f32_16x16x32_bf16 v[28:31], v[146:149], v[242:245], v[28:31]
	v_mfma_f32_16x16x32_bf16 v[28:31], v[142:145], v[234:237], v[28:31]
	v_mfma_f32_16x16x32_bf16 v[24:27], v[150:153], v[234:237], v[24:27]
	v_mfma_f32_16x16x32_bf16 v[24:27], v[174:177], v[242:245], v[24:27]
	v_mfma_f32_16x16x32_bf16 v[20:23], v[182:185], v[242:245], v[20:23]
	v_mfma_f32_16x16x32_bf16 v[20:23], v[178:181], v[234:237], v[20:23]
	v_mfma_f32_16x16x32_bf16 v[4:7], v[178:181], v[238:241], v[4:7]
	v_mfma_f32_16x16x32_bf16 v[4:7], v[182:185], v[246:249], v[4:7]
	v_mfma_f32_16x16x32_bf16 v[8:11], v[174:177], v[246:249], v[8:11]
	v_mfma_f32_16x16x32_bf16 v[8:11], v[150:153], v[238:241], v[8:11]
	v_mfma_f32_16x16x32_bf16 v[12:15], v[142:145], v[238:241], v[12:15]
	v_mfma_f32_16x16x32_bf16 v[12:15], v[146:149], v[246:249], v[12:15]
	v_mfma_f32_16x16x32_bf16 v[16:19], v[138:141], v[246:249], v[16:19]
	v_mfma_f32_16x16x32_bf16 v[16:19], v[134:137], v[238:241], v[16:19]
	s_barrier
	ds_read_b128 v[134:137], v213
	ds_read_b128 v[138:141], v214
	ds_read_b128 v[142:145], v209
	ds_read_b128 v[146:149], v210
	ds_read_b128 v[150:153], v215
	ds_read_b128 v[174:177], v216
	ds_read_b128 v[178:181], v211
	ds_read_b128 v[182:185], v212
	s_mov_b32 m0, s79
	v_lshl_add_u64 v[250:251], s[82:83], 0, v[0:1]
	ds_read_b128 v[218:221], v207 offset:32768
	ds_read_b128 v[222:225], v207 offset:34816
	ds_read_b128 v[226:229], v208 offset:32768
	ds_read_b128 v[230:233], v208 offset:34816
	ds_read_b128 v[234:237], v207 offset:36864
	ds_read_b128 v[238:241], v207 offset:38912
	ds_read_b128 v[242:245], v208 offset:36864
	ds_read_b128 v[246:249], v208 offset:38912
	global_load_lds_dwordx4 v[250:251], off
	v_lshl_add_u64 v[252:253], v[250:251], 0, s[20:21]
	s_mov_b32 m0, s81
	s_nop 0
	global_load_lds_dwordx4 v[252:253], off
	v_lshl_add_u64 v[252:253], v[250:251], 0, s[14:15]
	s_mov_b32 m0, s97
	v_lshl_add_u64 v[250:251], v[250:251], 0, s[22:23]
	global_load_lds_dwordx4 v[252:253], off
	s_mov_b32 m0, s64
	s_nop 0
	global_load_lds_dwordx4 v[250:251], off
	s_waitcnt vmcnt(8)
	s_waitcnt lgkmcnt(0)
	s_barrier
	v_mfma_f32_16x16x32_bf16 v[128:131], v[134:137], v[218:221], v[128:131]
	v_mfma_f32_16x16x32_bf16 v[128:131], v[138:141], v[226:229], v[128:131]
	v_mfma_f32_16x16x32_bf16 v[124:127], v[146:149], v[226:229], v[124:127]
	v_mfma_f32_16x16x32_bf16 v[124:127], v[142:145], v[218:221], v[124:127]
	v_mfma_f32_16x16x32_bf16 v[120:123], v[150:153], v[218:221], v[120:123]
	v_mfma_f32_16x16x32_bf16 v[120:123], v[174:177], v[226:229], v[120:123]
	v_mfma_f32_16x16x32_bf16 v[116:119], v[182:185], v[226:229], v[116:119]
	v_mfma_f32_16x16x32_bf16 v[116:119], v[178:181], v[218:221], v[116:119]
	v_mfma_f32_16x16x32_bf16 v[100:103], v[178:181], v[222:225], v[100:103]
	v_mfma_f32_16x16x32_bf16 v[100:103], v[182:185], v[230:233], v[100:103]
	v_mfma_f32_16x16x32_bf16 v[104:107], v[174:177], v[230:233], v[104:107]
	v_mfma_f32_16x16x32_bf16 v[104:107], v[150:153], v[222:225], v[104:107]
	v_mfma_f32_16x16x32_bf16 v[108:111], v[142:145], v[222:225], v[108:111]
	v_mfma_f32_16x16x32_bf16 v[108:111], v[146:149], v[230:233], v[108:111]
	v_mfma_f32_16x16x32_bf16 v[112:115], v[138:141], v[230:233], v[112:115]
	v_mfma_f32_16x16x32_bf16 v[112:115], v[134:137], v[222:225], v[112:115]
	v_mfma_f32_16x16x32_bf16 v[96:99], v[134:137], v[234:237], v[96:99]
	v_mfma_f32_16x16x32_bf16 v[96:99], v[138:141], v[242:245], v[96:99]
	v_mfma_f32_16x16x32_bf16 v[92:95], v[146:149], v[242:245], v[92:95]
	v_mfma_f32_16x16x32_bf16 v[92:95], v[142:145], v[234:237], v[92:95]
	v_mfma_f32_16x16x32_bf16 v[88:91], v[150:153], v[234:237], v[88:91]
	v_mfma_f32_16x16x32_bf16 v[88:91], v[174:177], v[242:245], v[88:91]
	v_mfma_f32_16x16x32_bf16 v[84:87], v[182:185], v[242:245], v[84:87]
	v_mfma_f32_16x16x32_bf16 v[84:87], v[178:181], v[234:237], v[84:87]
	v_mfma_f32_16x16x32_bf16 v[68:71], v[178:181], v[238:241], v[68:71]
	v_mfma_f32_16x16x32_bf16 v[68:71], v[182:185], v[246:249], v[68:71]
	v_mfma_f32_16x16x32_bf16 v[72:75], v[174:177], v[246:249], v[72:75]
	v_mfma_f32_16x16x32_bf16 v[72:75], v[150:153], v[238:241], v[72:75]
	v_mfma_f32_16x16x32_bf16 v[76:79], v[142:145], v[238:241], v[76:79]
	v_mfma_f32_16x16x32_bf16 v[76:79], v[146:149], v[246:249], v[76:79]
	v_mfma_f32_16x16x32_bf16 v[80:83], v[138:141], v[246:249], v[80:83]
	v_mfma_f32_16x16x32_bf16 v[80:83], v[134:137], v[238:241], v[80:83]
	s_barrier
	s_add_i32 s24, s70, s77
	v_lshl_add_u64 v[250:251], v[154:155], 0, s[48:49]
	s_mov_b32 m0, s24
	ds_read_b128 v[218:221], v207 offset:49152
	ds_read_b128 v[222:225], v207 offset:51200
	ds_read_b128 v[226:229], v208 offset:49152
	ds_read_b128 v[230:233], v208 offset:51200
	ds_read_b128 v[234:237], v207 offset:53248
	ds_read_b128 v[238:241], v207 offset:55296
	ds_read_b128 v[242:245], v208 offset:53248
	ds_read_b128 v[246:249], v208 offset:55296
	global_load_lds_dwordx4 v[250:251], off
	v_lshl_add_u64 v[250:251], v[154:155], 0, s[50:51]
	s_add_i32 m0, s24, 0x2000
	s_add_i32 s24, s71, s77
	global_load_lds_dwordx4 v[250:251], off
	v_lshl_add_u64 v[250:251], v[154:155], 0, s[52:53]
	s_mov_b32 m0, s24
	v_lshl_add_u64 v[154:155], v[154:155], 0, s[54:55]
	global_load_lds_dwordx4 v[250:251], off
	s_add_i32 m0, s24, 0x2000
	s_nop 0
	global_load_lds_dwordx4 v[154:155], off
	s_waitcnt vmcnt(4)
	s_waitcnt lgkmcnt(0)
	s_barrier
	v_mfma_f32_16x16x32_bf16 v[64:67], v[134:137], v[218:221], v[64:67]
	v_mfma_f32_16x16x32_bf16 v[64:67], v[138:141], v[226:229], v[64:67]
	v_mfma_f32_16x16x32_bf16 v[60:63], v[146:149], v[226:229], v[60:63]
	v_mfma_f32_16x16x32_bf16 v[60:63], v[142:145], v[218:221], v[60:63]
	v_mfma_f32_16x16x32_bf16 v[56:59], v[150:153], v[218:221], v[56:59]
	v_mfma_f32_16x16x32_bf16 v[56:59], v[174:177], v[226:229], v[56:59]
	v_mfma_f32_16x16x32_bf16 v[52:55], v[182:185], v[226:229], v[52:55]
	v_mfma_f32_16x16x32_bf16 v[52:55], v[178:181], v[218:221], v[52:55]
	v_mfma_f32_16x16x32_bf16 v[36:39], v[178:181], v[222:225], v[36:39]
	v_mfma_f32_16x16x32_bf16 v[36:39], v[182:185], v[230:233], v[36:39]
	v_mfma_f32_16x16x32_bf16 v[40:43], v[174:177], v[230:233], v[40:43]
	v_mfma_f32_16x16x32_bf16 v[40:43], v[150:153], v[222:225], v[40:43]
	v_mfma_f32_16x16x32_bf16 v[44:47], v[142:145], v[222:225], v[44:47]
	v_mfma_f32_16x16x32_bf16 v[44:47], v[146:149], v[230:233], v[44:47]
	v_mfma_f32_16x16x32_bf16 v[48:51], v[138:141], v[230:233], v[48:51]
	v_mfma_f32_16x16x32_bf16 v[48:51], v[134:137], v[222:225], v[48:51]
	v_mfma_f32_16x16x32_bf16 v[32:35], v[134:137], v[234:237], v[32:35]
	v_mfma_f32_16x16x32_bf16 v[32:35], v[138:141], v[242:245], v[32:35]
	v_mfma_f32_16x16x32_bf16 v[28:31], v[146:149], v[242:245], v[28:31]
	v_mfma_f32_16x16x32_bf16 v[28:31], v[142:145], v[234:237], v[28:31]
	v_mfma_f32_16x16x32_bf16 v[24:27], v[150:153], v[234:237], v[24:27]
	v_mfma_f32_16x16x32_bf16 v[24:27], v[174:177], v[242:245], v[24:27]
	v_mfma_f32_16x16x32_bf16 v[20:23], v[182:185], v[242:245], v[20:23]
	v_mfma_f32_16x16x32_bf16 v[20:23], v[178:181], v[234:237], v[20:23]
	v_mfma_f32_16x16x32_bf16 v[4:7], v[178:181], v[238:241], v[4:7]
	v_mfma_f32_16x16x32_bf16 v[4:7], v[182:185], v[246:249], v[4:7]
	v_mfma_f32_16x16x32_bf16 v[8:11], v[174:177], v[246:249], v[8:11]
	v_mfma_f32_16x16x32_bf16 v[8:11], v[150:153], v[238:241], v[8:11]
	v_mfma_f32_16x16x32_bf16 v[12:15], v[142:145], v[238:241], v[12:15]
	v_mfma_f32_16x16x32_bf16 v[12:15], v[146:149], v[246:249], v[12:15]
	v_mfma_f32_16x16x32_bf16 v[16:19], v[138:141], v[246:249], v[16:19]
	v_mfma_f32_16x16x32_bf16 v[16:19], v[134:137], v[238:241], v[16:19]
	s_barrier
	s_add_i32 s94, s94, 2
	s_add_u32 vcc_lo, vcc_lo, 0x100
	s_addc_u32 vcc_hi, vcc_hi, 0
	s_cmp_gt_u32 s94, 13
	s_cbranch_scc0 .LBB0_384
	s_and_b64 vcc, exec, s[56:57]
	s_cbranch_vccz .LBB0_387
	s_barrier

.LBB0_779:
	v_add_u32_e32 v4, s73, v159
	v_add_u32_e32 v6, s73, v173
	ds_read_b128 v[136:139], v4
	ds_read_b128 v[140:143], v6
	v_add_u32_e32 v4, s77, v159
	s_add_u32 s26, s28, s64
	v_add_u32_e32 v6, s77, v173
	ds_read_b128 v[180:183], v4
	ds_read_b128 v[196:199], v6
	v_add_u32_e32 v4, s79, v159
	s_addc_u32 s27, s29, s65
	v_add_u32_e32 v6, s79, v173
	ds_read_b128 v[200:203], v4
	ds_read_b128 v[204:207], v6
	v_add_u32_e32 v4, s80, v159
	s_add_u32 s26, s26, 0x100
	v_add_u32_e32 v6, s80, v173
	ds_read_b128 v[208:211], v4
	ds_read_b128 v[212:215], v6
	s_addc_u32 s27, s27, 0
	s_add_u32 s34, s93, s64
	s_addc_u32 s35, s94, s65
	s_cmpk_eq_i32 s64, 0xb00
	s_cselect_b32 s35, s63, s35
	s_cselect_b32 s34, s62, s34
	s_cselect_b32 s27, s1, s27
	s_cselect_b32 s26, s0, s26
	v_lshl_add_u64 v[6:7], v[170:171], 0, s[64:65]
	v_lshl_add_u64 v[184:185], v[6:7], 0, s[24:25]
	s_add_i32 m0, s66, 0x8000
	s_mov_b64 s[38:39], 0x30080
	ds_read_b128 v[216:219], v176
	ds_read_b128 v[220:223], v176 offset:2048
	ds_read_b128 v[224:227], v177
	ds_read_b128 v[228:231], v177 offset:2048
	ds_read_b128 v[232:235], v176 offset:4096
	ds_read_b128 v[236:239], v176 offset:6144
	ds_read_b128 v[240:243], v177 offset:4096
	ds_read_b128 v[244:247], v177 offset:6144
	global_load_lds_dwordx4 v[184:185], off
	v_lshl_add_u64 v[184:185], v[6:7], 0, s[38:39]
	s_add_i32 m0, s66, 0xa000
	s_mov_b64 s[38:39], 0x90080
	global_load_lds_dwordx4 v[184:185], off
	v_lshl_add_u64 v[184:185], v[6:7], 0, s[50:51]
	s_add_i32 m0, s66, 0xc000
	v_lshl_add_u64 v[6:7], v[6:7], 0, s[38:39]
	global_load_lds_dwordx4 v[184:185], off
	s_add_i32 m0, s66, 0xe000
	s_nop 0
	global_load_lds_dwordx4 v[6:7], off
	s_waitcnt vmcnt(8)
	s_waitcnt lgkmcnt(0)
	s_barrier
	v_mfma_f32_16x16x32_bf16 v[132:135], v[136:139], v[216:219], v[132:135]
	v_mfma_f32_16x16x32_bf16 v[132:135], v[140:143], v[224:227], v[132:135]
	v_mfma_f32_16x16x32_bf16 v[128:131], v[196:199], v[224:227], v[128:131]
	v_mfma_f32_16x16x32_bf16 v[128:131], v[180:183], v[216:219], v[128:131]
	v_mfma_f32_16x16x32_bf16 v[124:127], v[200:203], v[216:219], v[124:127]
	v_mfma_f32_16x16x32_bf16 v[124:127], v[204:207], v[224:227], v[124:127]
	v_mfma_f32_16x16x32_bf16 v[120:123], v[212:215], v[224:227], v[120:123]
	v_mfma_f32_16x16x32_bf16 v[120:123], v[208:211], v[216:219], v[120:123]
	v_mfma_f32_16x16x32_bf16 v[104:107], v[208:211], v[220:223], v[104:107]
	v_mfma_f32_16x16x32_bf16 v[104:107], v[212:215], v[228:231], v[104:107]
	v_mfma_f32_16x16x32_bf16 v[108:111], v[204:207], v[228:231], v[108:111]
	v_mfma_f32_16x16x32_bf16 v[108:111], v[200:203], v[220:223], v[108:111]
	v_mfma_f32_16x16x32_bf16 v[112:115], v[180:183], v[220:223], v[112:115]
	v_mfma_f32_16x16x32_bf16 v[112:115], v[196:199], v[228:231], v[112:115]
	v_mfma_f32_16x16x32_bf16 v[116:119], v[140:143], v[228:231], v[116:119]
	v_mfma_f32_16x16x32_bf16 v[116:119], v[136:139], v[220:223], v[116:119]
	v_mfma_f32_16x16x32_bf16 v[100:103], v[136:139], v[232:235], v[100:103]
	v_mfma_f32_16x16x32_bf16 v[100:103], v[140:143], v[240:243], v[100:103]
	v_mfma_f32_16x16x32_bf16 v[96:99], v[196:199], v[240:243], v[96:99]
	v_mfma_f32_16x16x32_bf16 v[96:99], v[180:183], v[232:235], v[96:99]
	v_mfma_f32_16x16x32_bf16 v[92:95], v[200:203], v[232:235], v[92:95]
	v_mfma_f32_16x16x32_bf16 v[92:95], v[204:207], v[240:243], v[92:95]
	v_mfma_f32_16x16x32_bf16 v[88:91], v[212:215], v[240:243], v[88:91]
	v_mfma_f32_16x16x32_bf16 v[88:91], v[208:211], v[232:235], v[88:91]
	v_mfma_f32_16x16x32_bf16 v[72:75], v[208:211], v[236:239], v[72:75]
	v_mfma_f32_16x16x32_bf16 v[72:75], v[212:215], v[244:247], v[72:75]
	v_mfma_f32_16x16x32_bf16 v[76:79], v[204:207], v[244:247], v[76:79]
	v_mfma_f32_16x16x32_bf16 v[76:79], v[200:203], v[236:239], v[76:79]
	v_mfma_f32_16x16x32_bf16 v[80:83], v[180:183], v[236:239], v[80:83]
	v_mfma_f32_16x16x32_bf16 v[80:83], v[196:199], v[244:247], v[80:83]
	v_mfma_f32_16x16x32_bf16 v[84:87], v[140:143], v[244:247], v[84:87]
	v_mfma_f32_16x16x32_bf16 v[84:87], v[136:139], v[236:239], v[84:87]
	s_barrier
	v_lshl_add_u64 v[184:185], s[34:35], 0, v[146:147]
	s_add_i32 s34, s73, s3
	s_mov_b32 m0, s34
	ds_read_b128 v[216:219], v176 offset:16384
	ds_read_b128 v[220:223], v176 offset:18432
	ds_read_b128 v[224:227], v177 offset:16384
	ds_read_b128 v[228:231], v177 offset:18432
	ds_read_b128 v[232:235], v176 offset:20480
	ds_read_b128 v[236:239], v176 offset:22528
	ds_read_b128 v[240:243], v177 offset:20480
	ds_read_b128 v[244:247], v177 offset:22528
	global_load_lds_dwordx4 v[184:185], off
	v_lshl_add_u64 v[6:7], v[184:185], 0, s[12:13]
	s_add_i32 m0, s34, 0x2000
	s_add_i32 s34, s79, s3
	global_load_lds_dwordx4 v[6:7], off
	v_lshl_add_u64 v[6:7], v[184:185], 0, s[14:15]
	s_mov_b32 m0, s34
	s_nop 0
	global_load_lds_dwordx4 v[6:7], off
	v_lshl_add_u64 v[6:7], v[184:185], 0, s[16:17]
	s_add_i32 m0, s34, 0x2000
	s_nop 0
	global_load_lds_dwordx4 v[6:7], off
	s_waitcnt vmcnt(4)
	s_waitcnt lgkmcnt(0)
	s_barrier
	v_mfma_f32_16x16x32_bf16 v[68:71], v[136:139], v[216:219], v[68:71]
	v_mfma_f32_16x16x32_bf16 v[68:71], v[140:143], v[224:227], v[68:71]
	v_mfma_f32_16x16x32_bf16 v[64:67], v[180:183], v[216:219], v[64:67]
	v_mfma_f32_16x16x32_bf16 v[64:67], v[196:199], v[224:227], v[64:67]
	v_mfma_f32_16x16x32_bf16 v[52:55], v[136:139], v[220:223], v[52:55]
	v_mfma_f32_16x16x32_bf16 v[52:55], v[140:143], v[228:231], v[52:55]
	v_mfma_f32_16x16x32_bf16 v[48:51], v[180:183], v[220:223], v[48:51]
	v_mfma_f32_16x16x32_bf16 v[48:51], v[196:199], v[228:231], v[48:51]
	v_mfma_f32_16x16x32_bf16 v[36:39], v[136:139], v[232:235], v[36:39]
	v_mfma_f32_16x16x32_bf16 v[36:39], v[140:143], v[240:243], v[36:39]
	v_mfma_f32_16x16x32_bf16 v[32:35], v[180:183], v[232:235], v[32:35]
	v_mfma_f32_16x16x32_bf16 v[32:35], v[196:199], v[240:243], v[32:35]
	v_mfma_f32_16x16x32_bf16 v[20:23], v[136:139], v[236:239], v[20:23]
	v_mfma_f32_16x16x32_bf16 v[20:23], v[140:143], v[244:247], v[20:23]
	v_mfma_f32_16x16x32_bf16 v[16:19], v[180:183], v[236:239], v[16:19]
	v_mfma_f32_16x16x32_bf16 v[16:19], v[196:199], v[244:247], v[16:19]
	v_mfma_f32_16x16x32_bf16 v[60:63], v[200:203], v[216:219], v[60:63]
	v_mfma_f32_16x16x32_bf16 v[60:63], v[204:207], v[224:227], v[60:63]
	v_mfma_f32_16x16x32_bf16 v[56:59], v[208:211], v[216:219], v[56:59]
	v_mfma_f32_16x16x32_bf16 v[56:59], v[212:215], v[224:227], v[56:59]
	v_mfma_f32_16x16x32_bf16 v[44:47], v[200:203], v[220:223], v[44:47]
	v_mfma_f32_16x16x32_bf16 v[44:47], v[204:207], v[228:231], v[44:47]
	v_mfma_f32_16x16x32_bf16 v[40:43], v[208:211], v[220:223], v[40:43]
	v_mfma_f32_16x16x32_bf16 v[40:43], v[212:215], v[228:231], v[40:43]
	v_mfma_f32_16x16x32_bf16 v[28:31], v[200:203], v[232:235], v[28:31]
	v_mfma_f32_16x16x32_bf16 v[28:31], v[204:207], v[240:243], v[28:31]
	v_mfma_f32_16x16x32_bf16 v[24:27], v[208:211], v[232:235], v[24:27]
	v_mfma_f32_16x16x32_bf16 v[24:27], v[212:215], v[240:243], v[24:27]
	v_mfma_f32_16x16x32_bf16 v[12:15], v[200:203], v[236:239], v[12:15]
	v_mfma_f32_16x16x32_bf16 v[12:15], v[204:207], v[244:247], v[12:15]
	v_mfma_f32_16x16x32_bf16 v[6:9], v[208:211], v[236:239], v[8:11]
	v_mfma_f32_16x16x32_bf16 v[6:9], v[212:215], v[244:247], v[6:9]
	s_barrier
	v_add_u32_e32 v4, s83, v159
	v_add_u32_e32 v10, s83, v173
	ds_read_b128 v[136:139], v4
	ds_read_b128 v[140:143], v10
	v_add_u32_e32 v4, s81, v159
	v_add_u32_e32 v10, s81, v173
	ds_read_b128 v[180:183], v4
	ds_read_b128 v[196:199], v10
	v_add_u32_e32 v4, s84, v159
	v_add_u32_e32 v10, s84, v173
	ds_read_b128 v[200:203], v4
	ds_read_b128 v[204:207], v10
	v_add_u32_e32 v4, s82, v159
	v_add_u32_e32 v10, s82, v173
	ds_read_b128 v[208:211], v4
	ds_read_b128 v[212:215], v10
	s_mov_b32 m0, s66
	v_lshl_add_u64 v[10:11], s[26:27], 0, v[144:145]
	ds_read_b128 v[216:219], v176 offset:32768
	ds_read_b128 v[220:223], v176 offset:34816
	ds_read_b128 v[224:227], v177 offset:32768
	ds_read_b128 v[228:231], v177 offset:34816
	ds_read_b128 v[232:235], v176 offset:36864
	ds_read_b128 v[236:239], v176 offset:38912
	ds_read_b128 v[240:243], v177 offset:36864
	ds_read_b128 v[244:247], v177 offset:38912
	global_load_lds_dwordx4 v[10:11], off
	v_lshl_add_u64 v[248:249], v[10:11], 0, s[18:19]
	s_mov_b32 m0, s67
	s_nop 0
	global_load_lds_dwordx4 v[248:249], off
	v_lshl_add_u64 v[248:249], v[10:11], 0, s[12:13]
	s_mov_b32 m0, s68
	v_lshl_add_u64 v[10:11], v[10:11], 0, s[20:21]
	global_load_lds_dwordx4 v[248:249], off
	s_mov_b32 m0, s69
	s_nop 0
	global_load_lds_dwordx4 v[10:11], off
	s_waitcnt vmcnt(8)
	s_waitcnt lgkmcnt(0)
	s_barrier
	v_mfma_f32_16x16x32_bf16 v[132:135], v[136:139], v[216:219], v[132:135]
	v_mfma_f32_16x16x32_bf16 v[132:135], v[140:143], v[224:227], v[132:135]
	v_mfma_f32_16x16x32_bf16 v[128:131], v[196:199], v[224:227], v[128:131]
	v_mfma_f32_16x16x32_bf16 v[128:131], v[180:183], v[216:219], v[128:131]
	v_mfma_f32_16x16x32_bf16 v[124:127], v[200:203], v[216:219], v[124:127]
	v_mfma_f32_16x16x32_bf16 v[124:127], v[204:207], v[224:227], v[124:127]
	v_mfma_f32_16x16x32_bf16 v[120:123], v[212:215], v[224:227], v[120:123]
	v_mfma_f32_16x16x32_bf16 v[120:123], v[208:211], v[216:219], v[120:123]
	v_mfma_f32_16x16x32_bf16 v[104:107], v[208:211], v[220:223], v[104:107]
	v_mfma_f32_16x16x32_bf16 v[104:107], v[212:215], v[228:231], v[104:107]
	v_mfma_f32_16x16x32_bf16 v[108:111], v[204:207], v[228:231], v[108:111]
	v_mfma_f32_16x16x32_bf16 v[108:111], v[200:203], v[220:223], v[108:111]
	v_mfma_f32_16x16x32_bf16 v[112:115], v[180:183], v[220:223], v[112:115]
	v_mfma_f32_16x16x32_bf16 v[112:115], v[196:199], v[228:231], v[112:115]
	v_mfma_f32_16x16x32_bf16 v[116:119], v[140:143], v[228:231], v[116:119]
	v_mfma_f32_16x16x32_bf16 v[116:119], v[136:139], v[220:223], v[116:119]
	v_mfma_f32_16x16x32_bf16 v[100:103], v[136:139], v[232:235], v[100:103]
	v_mfma_f32_16x16x32_bf16 v[100:103], v[140:143], v[240:243], v[100:103]
	v_mfma_f32_16x16x32_bf16 v[96:99], v[196:199], v[240:243], v[96:99]
	v_mfma_f32_16x16x32_bf16 v[96:99], v[180:183], v[232:235], v[96:99]
	v_mfma_f32_16x16x32_bf16 v[92:95], v[200:203], v[232:235], v[92:95]
	v_mfma_f32_16x16x32_bf16 v[92:95], v[204:207], v[240:243], v[92:95]
	v_mfma_f32_16x16x32_bf16 v[88:91], v[212:215], v[240:243], v[88:91]
	v_mfma_f32_16x16x32_bf16 v[88:91], v[208:211], v[232:235], v[88:91]
	v_mfma_f32_16x16x32_bf16 v[72:75], v[208:211], v[236:239], v[72:75]
	v_mfma_f32_16x16x32_bf16 v[72:75], v[212:215], v[244:247], v[72:75]
	v_mfma_f32_16x16x32_bf16 v[76:79], v[204:207], v[244:247], v[76:79]
	v_mfma_f32_16x16x32_bf16 v[76:79], v[200:203], v[236:239], v[76:79]
	v_mfma_f32_16x16x32_bf16 v[80:83], v[180:183], v[236:239], v[80:83]
	v_mfma_f32_16x16x32_bf16 v[80:83], v[196:199], v[244:247], v[80:83]
	v_mfma_f32_16x16x32_bf16 v[84:87], v[140:143], v[244:247], v[84:87]
	v_mfma_f32_16x16x32_bf16 v[84:87], v[136:139], v[236:239], v[84:87]
	s_barrier
	s_add_i32 s26, s83, s3
	v_lshl_add_u64 v[10:11], v[184:185], 0, s[24:25]
	s_mov_b32 m0, s26
	ds_read_b128 v[216:219], v176 offset:49152
	ds_read_b128 v[220:223], v176 offset:51200
	ds_read_b128 v[224:227], v177 offset:49152
	ds_read_b128 v[228:231], v177 offset:51200
	ds_read_b128 v[232:235], v176 offset:53248
	ds_read_b128 v[236:239], v176 offset:55296
	ds_read_b128 v[240:243], v177 offset:53248
	ds_read_b128 v[244:247], v177 offset:55296
	global_load_lds_dwordx4 v[10:11], off
	v_lshl_add_u64 v[10:11], v[184:185], 0, s[50:51]
	s_add_i32 m0, s26, 0x2000
	s_add_i32 s26, s84, s3
	global_load_lds_dwordx4 v[10:11], off
	v_lshl_add_u64 v[10:11], v[184:185], 0, s[52:53]
	s_mov_b32 m0, s26
	s_nop 0
	global_load_lds_dwordx4 v[10:11], off
	v_lshl_add_u64 v[10:11], v[184:185], 0, s[54:55]
	s_add_i32 m0, s26, 0x2000
	s_nop 0
	global_load_lds_dwordx4 v[10:11], off
	s_waitcnt vmcnt(4)
	s_waitcnt lgkmcnt(0)
	s_barrier
	v_mfma_f32_16x16x32_bf16 v[68:71], v[136:139], v[216:219], v[68:71]
	v_mfma_f32_16x16x32_bf16 v[68:71], v[140:143], v[224:227], v[68:71]
	v_mfma_f32_16x16x32_bf16 v[64:67], v[180:183], v[216:219], v[64:67]
	v_mfma_f32_16x16x32_bf16 v[64:67], v[196:199], v[224:227], v[64:67]
	v_mfma_f32_16x16x32_bf16 v[52:55], v[136:139], v[220:223], v[52:55]
	v_mfma_f32_16x16x32_bf16 v[52:55], v[140:143], v[228:231], v[52:55]
	v_mfma_f32_16x16x32_bf16 v[48:51], v[180:183], v[220:223], v[48:51]
	v_mfma_f32_16x16x32_bf16 v[48:51], v[196:199], v[228:231], v[48:51]
	v_mfma_f32_16x16x32_bf16 v[36:39], v[136:139], v[232:235], v[36:39]
	v_mfma_f32_16x16x32_bf16 v[36:39], v[140:143], v[240:243], v[36:39]
	v_mfma_f32_16x16x32_bf16 v[32:35], v[180:183], v[232:235], v[32:35]
	v_mfma_f32_16x16x32_bf16 v[32:35], v[196:199], v[240:243], v[32:35]
	v_mfma_f32_16x16x32_bf16 v[20:23], v[136:139], v[236:239], v[20:23]
	v_mfma_f32_16x16x32_bf16 v[20:23], v[140:143], v[244:247], v[20:23]
	v_mfma_f32_16x16x32_bf16 v[16:19], v[180:183], v[236:239], v[16:19]
	v_mfma_f32_16x16x32_bf16 v[16:19], v[196:199], v[244:247], v[16:19]
	v_mfma_f32_16x16x32_bf16 v[60:63], v[200:203], v[216:219], v[60:63]
	v_mfma_f32_16x16x32_bf16 v[60:63], v[204:207], v[224:227], v[60:63]
	v_mfma_f32_16x16x32_bf16 v[56:59], v[208:211], v[216:219], v[56:59]
	v_mfma_f32_16x16x32_bf16 v[56:59], v[212:215], v[224:227], v[56:59]
	v_mfma_f32_16x16x32_bf16 v[44:47], v[200:203], v[220:223], v[44:47]
	v_mfma_f32_16x16x32_bf16 v[44:47], v[204:207], v[228:231], v[44:47]
	v_mfma_f32_16x16x32_bf16 v[40:43], v[208:211], v[220:223], v[40:43]
	v_mfma_f32_16x16x32_bf16 v[40:43], v[212:215], v[228:231], v[40:43]
	v_mfma_f32_16x16x32_bf16 v[28:31], v[200:203], v[232:235], v[28:31]
	v_mfma_f32_16x16x32_bf16 v[28:31], v[204:207], v[240:243], v[28:31]
	v_mfma_f32_16x16x32_bf16 v[24:27], v[208:211], v[232:235], v[24:27]
	v_mfma_f32_16x16x32_bf16 v[24:27], v[212:215], v[240:243], v[24:27]
	v_mfma_f32_16x16x32_bf16 v[10:13], v[200:203], v[236:239], v[12:15]
	v_mfma_f32_16x16x32_bf16 v[12:15], v[204:207], v[244:247], v[10:13]
	v_mfma_f32_16x16x32_bf16 v[6:9], v[208:211], v[236:239], v[6:9]
	v_mfma_f32_16x16x32_bf16 v[8:11], v[212:215], v[244:247], v[6:9]
	s_barrier
	s_add_i32 s95, s95, 2
	s_add_u32 s64, s64, 0x100
	s_addc_u32 s65, s65, 0
	s_cmp_gt_u32 s95, 21
	s_cbranch_scc1 .LBB0_782

.LBB0_973:
	v_add_u32_e32 v133, s72, v163
	v_add_u32_e32 v140, s72, v164
	ds_read_b128 v[136:139], v133
	ds_read_b128 v[148:151], v140
	v_add_u32_e32 v133, s73, v163
	s_add_u32 s70, s28, s26
	v_add_u32_e32 v140, s73, v164
	s_waitcnt lgkmcnt(0)
	ds_read_b128 v[152:155], v133
	ds_read_b128 v[174:177], v140
	v_add_u32_e32 v133, s77, v163
	s_addc_u32 s71, s29, s27
	v_add_u32_e32 v140, s77, v164
	ds_read_b128 v[178:181], v133
	ds_read_b128 v[182:185], v140
	v_add_u32_e32 v133, s79, v163
	s_add_u32 s70, s70, 0x100
	v_add_u32_e32 v140, s79, v164
	ds_read_b128 v[196:199], v133
	ds_read_b128 v[200:203], v140
	s_addc_u32 s71, s71, 0
	s_add_u32 s86, s65, s26
	s_addc_u32 s87, s85, s27
	s_cmpk_eq_i32 s26, 0x700
	s_cselect_b32 s87, s61, s87
	s_cselect_b32 s86, s88, s86
	s_cselect_b32 s71, s54, s71
	s_cselect_b32 s70, s63, s70
	v_lshl_add_u64 v[140:141], v[134:135], 0, s[26:27]
	v_lshl_add_u64 v[160:161], v[140:141], 0, s[36:37]
	s_add_i32 m0, s5, 0x8000
	s_mov_b64 s[90:91], 0x20080
	ds_read_b128 v[204:207], v166
	ds_read_b128 v[208:211], v166 offset:2048
	ds_read_b128 v[212:215], v167
	ds_read_b128 v[216:219], v167 offset:2048
	ds_read_b128 v[220:223], v166 offset:4096
	ds_read_b128 v[224:227], v166 offset:6144
	ds_read_b128 v[228:231], v167 offset:4096
	ds_read_b128 v[232:235], v167 offset:6144
	global_load_lds_dwordx4 v[160:161], off
	v_lshl_add_u64 v[160:161], v[140:141], 0, s[90:91]
	s_add_i32 m0, s5, 0xa000
	s_mov_b64 s[90:91], 0x60080
	global_load_lds_dwordx4 v[160:161], off
	v_lshl_add_u64 v[160:161], v[140:141], 0, s[44:45]
	s_add_i32 m0, s5, 0xc000
	v_lshl_add_u64 v[140:141], v[140:141], 0, s[90:91]
	global_load_lds_dwordx4 v[160:161], off
	s_add_i32 m0, s5, 0xe000
	s_nop 0
	global_load_lds_dwordx4 v[140:141], off
	s_waitcnt vmcnt(8)
	s_waitcnt lgkmcnt(0)
	s_barrier
	v_mfma_f32_16x16x32_bf16 v[8:11], v[136:139], v[204:207], v[8:11]
	v_mfma_f32_16x16x32_bf16 v[8:11], v[148:151], v[212:215], v[8:11]
	v_mfma_f32_16x16x32_bf16 v[4:7], v[174:177], v[212:215], v[4:7]
	v_mfma_f32_16x16x32_bf16 v[4:7], v[152:155], v[204:207], v[4:7]
	v_mfma_f32_16x16x32_bf16 v[32:35], v[178:181], v[204:207], v[32:35]
	v_mfma_f32_16x16x32_bf16 v[32:35], v[182:185], v[212:215], v[32:35]
	v_mfma_f32_16x16x32_bf16 v[28:31], v[200:203], v[212:215], v[28:31]
	v_mfma_f32_16x16x32_bf16 v[28:31], v[196:199], v[204:207], v[28:31]
	v_mfma_f32_16x16x32_bf16 v[52:55], v[196:199], v[208:211], v[52:55]
	v_mfma_f32_16x16x32_bf16 v[52:55], v[200:203], v[216:219], v[52:55]
	v_mfma_f32_16x16x32_bf16 v[40:43], v[182:185], v[216:219], v[40:43]
	v_mfma_f32_16x16x32_bf16 v[40:43], v[178:181], v[208:211], v[40:43]
	v_mfma_f32_16x16x32_bf16 v[16:19], v[152:155], v[208:211], v[16:19]
	v_mfma_f32_16x16x32_bf16 v[16:19], v[174:177], v[216:219], v[16:19]
	v_mfma_f32_16x16x32_bf16 v[12:15], v[148:151], v[216:219], v[12:15]
	v_mfma_f32_16x16x32_bf16 v[12:15], v[136:139], v[208:211], v[12:15]
	v_mfma_f32_16x16x32_bf16 v[44:47], v[136:139], v[220:223], v[44:47]
	v_mfma_f32_16x16x32_bf16 v[44:47], v[148:151], v[228:231], v[44:47]
	v_mfma_f32_16x16x32_bf16 v[36:39], v[174:177], v[228:231], v[36:39]
	v_mfma_f32_16x16x32_bf16 v[36:39], v[152:155], v[220:223], v[36:39]
	v_mfma_f32_16x16x32_bf16 v[48:51], v[178:181], v[220:223], v[48:51]
	v_mfma_f32_16x16x32_bf16 v[48:51], v[182:185], v[228:231], v[48:51]
	v_mfma_f32_16x16x32_bf16 v[60:63], v[200:203], v[228:231], v[60:63]
	v_mfma_f32_16x16x32_bf16 v[60:63], v[196:199], v[220:223], v[60:63]
	v_mfma_f32_16x16x32_bf16 v[64:67], v[196:199], v[224:227], v[64:67]
	v_mfma_f32_16x16x32_bf16 v[64:67], v[200:203], v[232:235], v[64:67]
	v_mfma_f32_16x16x32_bf16 v[56:59], v[182:185], v[232:235], v[56:59]
	v_mfma_f32_16x16x32_bf16 v[56:59], v[178:181], v[224:227], v[56:59]
	v_mfma_f32_16x16x32_bf16 v[24:27], v[152:155], v[224:227], v[24:27]
	v_mfma_f32_16x16x32_bf16 v[24:27], v[174:177], v[232:235], v[24:27]
	v_mfma_f32_16x16x32_bf16 v[20:23], v[148:151], v[232:235], v[20:23]
	v_mfma_f32_16x16x32_bf16 v[20:23], v[136:139], v[224:227], v[20:23]
	s_barrier
	v_lshl_add_u64 v[140:141], s[86:87], 0, v[158:159]
	s_add_i32 s86, s72, s34
	s_mov_b32 m0, s86
	ds_read_b128 v[204:207], v166 offset:16384
	ds_read_b128 v[208:211], v166 offset:18432
	ds_read_b128 v[212:215], v167 offset:16384
	ds_read_b128 v[216:219], v167 offset:18432
	ds_read_b128 v[220:223], v166 offset:20480
	ds_read_b128 v[224:227], v166 offset:22528
	ds_read_b128 v[228:231], v167 offset:20480
	ds_read_b128 v[232:235], v167 offset:22528
	global_load_lds_dwordx4 v[140:141], off
	v_lshl_add_u64 v[160:161], v[140:141], 0, s[18:19]
	s_add_i32 m0, s86, 0x2000
	s_mov_b64 s[86:87], 0x10000
	global_load_lds_dwordx4 v[160:161], off
	v_lshl_add_u64 v[160:161], v[140:141], 0, s[86:87]
	s_add_i32 s86, s77, s34
	s_mov_b32 m0, s86
	s_nop 0
	global_load_lds_dwordx4 v[160:161], off
	v_lshl_add_u64 v[160:161], v[140:141], 0, s[20:21]
	s_add_i32 m0, s86, 0x2000
	s_nop 0
	global_load_lds_dwordx4 v[160:161], off
	s_waitcnt vmcnt(4)
	s_waitcnt lgkmcnt(0)
	s_barrier
	v_mfma_f32_16x16x32_bf16 v[68:71], v[136:139], v[204:207], v[68:71]
	v_mfma_f32_16x16x32_bf16 v[68:71], v[148:151], v[212:215], v[68:71]
	v_mfma_f32_16x16x32_bf16 v[72:75], v[174:177], v[212:215], v[72:75]
	v_mfma_f32_16x16x32_bf16 v[72:75], v[152:155], v[204:207], v[72:75]
	v_mfma_f32_16x16x32_bf16 v[88:91], v[178:181], v[204:207], v[88:91]
	v_mfma_f32_16x16x32_bf16 v[88:91], v[182:185], v[212:215], v[88:91]
	v_mfma_f32_16x16x32_bf16 v[100:103], v[200:203], v[212:215], v[100:103]
	v_mfma_f32_16x16x32_bf16 v[100:103], v[196:199], v[204:207], v[100:103]
	v_mfma_f32_16x16x32_bf16 v[104:107], v[196:199], v[208:211], v[104:107]
	v_mfma_f32_16x16x32_bf16 v[104:107], v[200:203], v[216:219], v[104:107]
	v_mfma_f32_16x16x32_bf16 v[96:99], v[182:185], v[216:219], v[96:99]
	v_mfma_f32_16x16x32_bf16 v[96:99], v[178:181], v[208:211], v[96:99]
	v_mfma_f32_16x16x32_bf16 v[84:87], v[152:155], v[208:211], v[84:87]
	v_mfma_f32_16x16x32_bf16 v[84:87], v[174:177], v[216:219], v[84:87]
	v_mfma_f32_16x16x32_bf16 v[92:95], v[148:151], v[216:219], v[92:95]
	v_mfma_f32_16x16x32_bf16 v[92:95], v[136:139], v[208:211], v[92:95]
	v_mfma_f32_16x16x32_bf16 v[76:79], v[136:139], v[220:223], v[76:79]
	v_mfma_f32_16x16x32_bf16 v[76:79], v[148:151], v[228:231], v[76:79]
	v_mfma_f32_16x16x32_bf16 v[80:83], v[174:177], v[228:231], v[80:83]
	v_mfma_f32_16x16x32_bf16 v[80:83], v[152:155], v[220:223], v[80:83]
	v_mfma_f32_16x16x32_bf16 v[112:115], v[178:181], v[220:223], v[112:115]
	v_mfma_f32_16x16x32_bf16 v[112:115], v[182:185], v[228:231], v[112:115]
	v_mfma_f32_16x16x32_bf16 v[124:127], v[200:203], v[228:231], v[124:127]
	v_mfma_f32_16x16x32_bf16 v[124:127], v[196:199], v[220:223], v[124:127]
	v_mfma_f32_16x16x32_bf16 v[128:131], v[196:199], v[224:227], v[128:131]
	v_mfma_f32_16x16x32_bf16 v[128:131], v[200:203], v[232:235], v[128:131]
	v_mfma_f32_16x16x32_bf16 v[120:123], v[182:185], v[232:235], v[120:123]
	v_mfma_f32_16x16x32_bf16 v[120:123], v[178:181], v[224:227], v[120:123]
	v_mfma_f32_16x16x32_bf16 v[108:111], v[152:155], v[224:227], v[108:111]
	v_mfma_f32_16x16x32_bf16 v[108:111], v[174:177], v[232:235], v[108:111]
	v_mfma_f32_16x16x32_bf16 v[116:119], v[148:151], v[232:235], v[116:119]
	v_mfma_f32_16x16x32_bf16 v[116:119], v[136:139], v[224:227], v[116:119]
	s_barrier
	v_add_u32_e32 v133, s82, v163
	v_add_u32_e32 v148, s82, v164
	ds_read_b128 v[136:139], v133
	ds_read_b128 v[148:151], v148
	v_add_u32_e32 v133, s80, v163
	v_add_u32_e32 v160, s80, v164
	ds_read_b128 v[152:155], v133
	ds_read_b128 v[174:177], v160
	v_add_u32_e32 v133, s83, v163
	v_add_u32_e32 v160, s83, v164
	ds_read_b128 v[178:181], v133
	ds_read_b128 v[182:185], v160
	v_add_u32_e32 v133, s81, v163
	v_add_u32_e32 v160, s81, v164
	ds_read_b128 v[196:199], v133
	ds_read_b128 v[200:203], v160
	s_mov_b32 m0, s5
	v_lshl_add_u64 v[160:161], s[70:71], 0, v[0:1]
	s_mov_b64 s[70:71], 0x20000
	ds_read_b128 v[204:207], v166 offset:32768
	ds_read_b128 v[208:211], v166 offset:34816
	ds_read_b128 v[212:215], v167 offset:32768
	ds_read_b128 v[216:219], v167 offset:34816
	ds_read_b128 v[220:223], v166 offset:36864
	ds_read_b128 v[224:227], v166 offset:38912
	ds_read_b128 v[228:231], v167 offset:36864
	ds_read_b128 v[232:235], v167 offset:38912
	global_load_lds_dwordx4 v[160:161], off
	v_lshl_add_u64 v[170:171], v[160:161], 0, s[70:71]
	s_mov_b32 m0, s17
	s_nop 0
	global_load_lds_dwordx4 v[170:171], off
	v_lshl_add_u64 v[170:171], v[160:161], 0, s[18:19]
	s_mov_b32 m0, s35
	v_lshl_add_u64 v[160:161], v[160:161], 0, s[22:23]
	global_load_lds_dwordx4 v[170:171], off
	s_mov_b32 m0, s38
	s_nop 0
	global_load_lds_dwordx4 v[160:161], off
	s_waitcnt vmcnt(8)
	s_waitcnt lgkmcnt(0)
	s_barrier
	v_mfma_f32_16x16x32_bf16 v[8:11], v[136:139], v[204:207], v[8:11]
	v_mfma_f32_16x16x32_bf16 v[8:11], v[148:151], v[212:215], v[8:11]
	v_mfma_f32_16x16x32_bf16 v[4:7], v[174:177], v[212:215], v[4:7]
	v_mfma_f32_16x16x32_bf16 v[4:7], v[152:155], v[204:207], v[4:7]
	v_mfma_f32_16x16x32_bf16 v[32:35], v[178:181], v[204:207], v[32:35]
	v_mfma_f32_16x16x32_bf16 v[32:35], v[182:185], v[212:215], v[32:35]
	v_mfma_f32_16x16x32_bf16 v[28:31], v[200:203], v[212:215], v[28:31]
	v_mfma_f32_16x16x32_bf16 v[28:31], v[196:199], v[204:207], v[28:31]
	v_mfma_f32_16x16x32_bf16 v[52:55], v[196:199], v[208:211], v[52:55]
	v_mfma_f32_16x16x32_bf16 v[52:55], v[200:203], v[216:219], v[52:55]
	v_mfma_f32_16x16x32_bf16 v[40:43], v[182:185], v[216:219], v[40:43]
	v_mfma_f32_16x16x32_bf16 v[40:43], v[178:181], v[208:211], v[40:43]
	v_mfma_f32_16x16x32_bf16 v[16:19], v[152:155], v[208:211], v[16:19]
	v_mfma_f32_16x16x32_bf16 v[16:19], v[174:177], v[216:219], v[16:19]
	v_mfma_f32_16x16x32_bf16 v[12:15], v[148:151], v[216:219], v[12:15]
	v_mfma_f32_16x16x32_bf16 v[12:15], v[136:139], v[208:211], v[12:15]
	v_mfma_f32_16x16x32_bf16 v[44:47], v[136:139], v[220:223], v[44:47]
	v_mfma_f32_16x16x32_bf16 v[44:47], v[148:151], v[228:231], v[44:47]
	v_mfma_f32_16x16x32_bf16 v[36:39], v[174:177], v[228:231], v[36:39]
	v_mfma_f32_16x16x32_bf16 v[36:39], v[152:155], v[220:223], v[36:39]
	v_mfma_f32_16x16x32_bf16 v[48:51], v[178:181], v[220:223], v[48:51]
	v_mfma_f32_16x16x32_bf16 v[48:51], v[182:185], v[228:231], v[48:51]
	v_mfma_f32_16x16x32_bf16 v[60:63], v[200:203], v[228:231], v[60:63]
	v_mfma_f32_16x16x32_bf16 v[60:63], v[196:199], v[220:223], v[60:63]
	v_mfma_f32_16x16x32_bf16 v[64:67], v[196:199], v[224:227], v[64:67]
	v_mfma_f32_16x16x32_bf16 v[64:67], v[200:203], v[232:235], v[64:67]
	v_mfma_f32_16x16x32_bf16 v[56:59], v[182:185], v[232:235], v[56:59]
	v_mfma_f32_16x16x32_bf16 v[56:59], v[178:181], v[224:227], v[56:59]
	v_mfma_f32_16x16x32_bf16 v[24:27], v[152:155], v[224:227], v[24:27]
	v_mfma_f32_16x16x32_bf16 v[24:27], v[174:177], v[232:235], v[24:27]
	v_mfma_f32_16x16x32_bf16 v[20:23], v[148:151], v[232:235], v[20:23]
	v_mfma_f32_16x16x32_bf16 v[20:23], v[136:139], v[224:227], v[20:23]
	s_barrier
	s_add_i32 s70, s82, s34
	v_lshl_add_u64 v[160:161], v[140:141], 0, s[36:37]
	s_mov_b32 m0, s70
	ds_read_b128 v[204:207], v166 offset:49152
	ds_read_b128 v[208:211], v166 offset:51200
	ds_read_b128 v[212:215], v167 offset:49152
	ds_read_b128 v[216:219], v167 offset:51200
	ds_read_b128 v[220:223], v166 offset:53248
	ds_read_b128 v[224:227], v166 offset:55296
	ds_read_b128 v[228:231], v167 offset:53248
	ds_read_b128 v[232:235], v167 offset:55296
	global_load_lds_dwordx4 v[160:161], off
	v_lshl_add_u64 v[160:161], v[140:141], 0, s[44:45]
	s_add_i32 m0, s70, 0x2000
	s_add_i32 s70, s83, s34
	global_load_lds_dwordx4 v[160:161], off
	v_lshl_add_u64 v[160:161], v[140:141], 0, s[46:47]
	s_mov_b32 m0, s70
	v_lshl_add_u64 v[140:141], v[140:141], 0, s[50:51]
	global_load_lds_dwordx4 v[160:161], off
	s_add_i32 m0, s70, 0x2000
	s_nop 0
	global_load_lds_dwordx4 v[140:141], off
	s_waitcnt vmcnt(4)
	s_waitcnt lgkmcnt(0)
	s_barrier
	v_mfma_f32_16x16x32_bf16 v[68:71], v[136:139], v[204:207], v[68:71]
	v_mfma_f32_16x16x32_bf16 v[68:71], v[148:151], v[212:215], v[68:71]
	v_mfma_f32_16x16x32_bf16 v[72:75], v[174:177], v[212:215], v[72:75]
	v_mfma_f32_16x16x32_bf16 v[72:75], v[152:155], v[204:207], v[72:75]
	v_mfma_f32_16x16x32_bf16 v[88:91], v[178:181], v[204:207], v[88:91]
	v_mfma_f32_16x16x32_bf16 v[88:91], v[182:185], v[212:215], v[88:91]
	v_mfma_f32_16x16x32_bf16 v[100:103], v[200:203], v[212:215], v[100:103]
	v_mfma_f32_16x16x32_bf16 v[100:103], v[196:199], v[204:207], v[100:103]
	v_mfma_f32_16x16x32_bf16 v[104:107], v[196:199], v[208:211], v[104:107]
	v_mfma_f32_16x16x32_bf16 v[104:107], v[200:203], v[216:219], v[104:107]
	v_mfma_f32_16x16x32_bf16 v[96:99], v[182:185], v[216:219], v[96:99]
	v_mfma_f32_16x16x32_bf16 v[96:99], v[178:181], v[208:211], v[96:99]
	v_mfma_f32_16x16x32_bf16 v[84:87], v[152:155], v[208:211], v[84:87]
	v_mfma_f32_16x16x32_bf16 v[84:87], v[174:177], v[216:219], v[84:87]
	v_mfma_f32_16x16x32_bf16 v[92:95], v[148:151], v[216:219], v[92:95]
	v_mfma_f32_16x16x32_bf16 v[92:95], v[136:139], v[208:211], v[92:95]
	v_mfma_f32_16x16x32_bf16 v[76:79], v[136:139], v[220:223], v[76:79]
	v_mfma_f32_16x16x32_bf16 v[76:79], v[148:151], v[228:231], v[76:79]
	v_mfma_f32_16x16x32_bf16 v[80:83], v[174:177], v[228:231], v[80:83]
	v_mfma_f32_16x16x32_bf16 v[80:83], v[152:155], v[220:223], v[80:83]
	v_mfma_f32_16x16x32_bf16 v[112:115], v[178:181], v[220:223], v[112:115]
	v_mfma_f32_16x16x32_bf16 v[112:115], v[182:185], v[228:231], v[112:115]
	v_mfma_f32_16x16x32_bf16 v[124:127], v[200:203], v[228:231], v[124:127]
	v_mfma_f32_16x16x32_bf16 v[124:127], v[196:199], v[220:223], v[124:127]
	v_mfma_f32_16x16x32_bf16 v[128:131], v[196:199], v[224:227], v[128:131]
	v_mfma_f32_16x16x32_bf16 v[128:131], v[200:203], v[232:235], v[128:131]
	v_mfma_f32_16x16x32_bf16 v[120:123], v[182:185], v[232:235], v[120:123]
	v_mfma_f32_16x16x32_bf16 v[120:123], v[178:181], v[224:227], v[120:123]
	v_mfma_f32_16x16x32_bf16 v[108:111], v[152:155], v[224:227], v[108:111]
	v_mfma_f32_16x16x32_bf16 v[108:111], v[174:177], v[232:235], v[108:111]
	v_mfma_f32_16x16x32_bf16 v[116:119], v[148:151], v[232:235], v[116:119]
	v_mfma_f32_16x16x32_bf16 v[116:119], v[136:139], v[224:227], v[116:119]
	s_barrier
	s_add_i32 s89, s89, 2
	s_add_u32 s26, s26, 0x100
	s_addc_u32 s27, s27, 0
	s_cmp_gt_u32 s89, 13
	s_cbranch_scc0 .LBB0_973
	s_and_b64 vcc, exec, s[52:53]
	s_cbranch_vccz .LBB0_976
	s_barrier

.LBB0_1134:
	s_ashr_i32 s57, s56, 31
	s_lshl_b64 s[60:61], s[56:57], 19
	s_add_u32 s60, s42, s60
	s_addc_u32 s61, s43, s61
	s_and_b64 s[62:63], s[10:11], exec
	s_cselect_b32 s57, s61, s27
	s_cselect_b32 s79, s60, s26
	s_ashr_i32 s59, s58, 31
	s_lshl_b64 s[62:63], s[58:59], 19
	v_readlane_b32 s70, v254, 7
	v_readlane_b32 s71, v254, 8
	s_add_u32 s62, s70, s62
	s_addc_u32 s63, s71, s63
	s_and_b64 s[70:71], s[10:11], exec
	s_cselect_b32 s59, s63, s69
	s_cselect_b32 s80, s62, s68
	s_add_u32 s81, s68, 0x100
	v_lshl_add_u64 v[138:139], s[26:27], 0, v[132:133]
	s_addc_u32 s82, s69, 0
	s_mov_b32 s83, -2
	s_mov_b64 s[68:69], 0
	ds_read_b128 v[168:171], v145
	ds_read_b128 v[174:177], v146
	ds_read_b128 v[178:181], v147
	ds_read_b128 v[182:185], v148
	ds_read_b128 v[194:197], v149
	ds_read_b128 v[198:201], v150
	ds_read_b128 v[202:205], v151
	ds_read_b128 v[206:209], v152
	s_add_u32 s70, s26, s68
	s_addc_u32 s71, s27, s69
	s_add_u32 s70, s70, 0x100
	s_addc_u32 s71, s71, 0
	s_add_u32 s84, s81, s68
	s_addc_u32 s85, s82, s69
	s_cmpk_eq_i32 s68, 0x700
	s_cselect_b32 s85, s59, s85
	s_cselect_b32 s84, s80, s84
	s_cselect_b32 s71, s57, s71
	s_cselect_b32 s70, s79, s70
	v_lshl_add_u64 v[140:141], v[138:139], 0, s[68:69]
	v_lshl_add_u64 v[242:243], v[140:141], 0, s[22:23]
	s_add_i32 m0, s34, 0x8000
	s_mov_b64 s[86:87], 0x20080
	ds_read_b128 v[210:213], v153
	ds_read_b128 v[214:217], v153 offset:2048
	ds_read_b128 v[218:221], v154
	ds_read_b128 v[222:225], v154 offset:2048
	ds_read_b128 v[226:229], v153 offset:4096
	ds_read_b128 v[230:233], v153 offset:6144
	ds_read_b128 v[234:237], v154 offset:4096
	ds_read_b128 v[238:241], v154 offset:6144
	global_load_lds_dwordx4 v[242:243], off
	v_lshl_add_u64 v[242:243], v[140:141], 0, s[86:87]
	s_add_i32 m0, s34, 0xa000
	s_mov_b64 s[86:87], 0x60080
	global_load_lds_dwordx4 v[242:243], off
	v_lshl_add_u64 v[242:243], v[140:141], 0, s[24:25]
	s_add_i32 m0, s34, 0xc000
	v_lshl_add_u64 v[140:141], v[140:141], 0, s[86:87]
	global_load_lds_dwordx4 v[242:243], off
	s_add_i32 m0, s34, 0xe000
	s_nop 0
	global_load_lds_dwordx4 v[140:141], off
	s_waitcnt lgkmcnt(0)
	s_barrier
	v_mfma_f32_16x16x32_bf16 v[128:131], v[168:171], v[210:213], 0
	v_mfma_f32_16x16x32_bf16 v[128:131], v[174:177], v[218:221], v[128:131]
	v_mfma_f32_16x16x32_bf16 v[124:127], v[178:181], v[210:213], 0
	v_mfma_f32_16x16x32_bf16 v[124:127], v[182:185], v[218:221], v[124:127]
	v_mfma_f32_16x16x32_bf16 v[120:123], v[194:197], v[210:213], 0
	v_mfma_f32_16x16x32_bf16 v[120:123], v[198:201], v[218:221], v[120:123]
	v_mfma_f32_16x16x32_bf16 v[116:119], v[202:205], v[210:213], 0
	v_mfma_f32_16x16x32_bf16 v[116:119], v[206:209], v[218:221], v[116:119]
	v_mfma_f32_16x16x32_bf16 v[100:103], v[202:205], v[214:217], 0
	v_mfma_f32_16x16x32_bf16 v[100:103], v[206:209], v[222:225], v[100:103]
	v_mfma_f32_16x16x32_bf16 v[104:107], v[194:197], v[214:217], 0
	v_mfma_f32_16x16x32_bf16 v[104:107], v[198:201], v[222:225], v[104:107]
	v_mfma_f32_16x16x32_bf16 v[108:111], v[178:181], v[214:217], 0
	v_mfma_f32_16x16x32_bf16 v[108:111], v[182:185], v[222:225], v[108:111]
	v_mfma_f32_16x16x32_bf16 v[112:115], v[168:171], v[214:217], 0
	v_mfma_f32_16x16x32_bf16 v[112:115], v[174:177], v[222:225], v[112:115]
	v_mfma_f32_16x16x32_bf16 v[96:99], v[168:171], v[226:229], 0
	v_mfma_f32_16x16x32_bf16 v[96:99], v[174:177], v[234:237], v[96:99]
	v_mfma_f32_16x16x32_bf16 v[92:95], v[178:181], v[226:229], 0
	v_mfma_f32_16x16x32_bf16 v[92:95], v[182:185], v[234:237], v[92:95]
	v_mfma_f32_16x16x32_bf16 v[88:91], v[194:197], v[226:229], 0
	v_mfma_f32_16x16x32_bf16 v[88:91], v[198:201], v[234:237], v[88:91]
	v_mfma_f32_16x16x32_bf16 v[84:87], v[202:205], v[226:229], 0
	v_mfma_f32_16x16x32_bf16 v[84:87], v[206:209], v[234:237], v[84:87]
	v_mfma_f32_16x16x32_bf16 v[68:71], v[202:205], v[230:233], 0
	v_mfma_f32_16x16x32_bf16 v[68:71], v[206:209], v[238:241], v[68:71]
	v_mfma_f32_16x16x32_bf16 v[72:75], v[194:197], v[230:233], 0
	v_mfma_f32_16x16x32_bf16 v[72:75], v[198:201], v[238:241], v[72:75]
	v_mfma_f32_16x16x32_bf16 v[76:79], v[178:181], v[230:233], 0
	v_mfma_f32_16x16x32_bf16 v[76:79], v[182:185], v[238:241], v[76:79]
	v_mfma_f32_16x16x32_bf16 v[80:83], v[168:171], v[230:233], 0
	v_mfma_f32_16x16x32_bf16 v[80:83], v[174:177], v[238:241], v[80:83]
	s_barrier
	v_lshl_add_u64 v[140:141], s[84:85], 0, v[158:159]
	s_add_i32 s84, s67, s3
	s_mov_b32 m0, s84
	ds_read_b128 v[210:213], v153 offset:16384
	ds_read_b128 v[214:217], v153 offset:18432
	ds_read_b128 v[218:221], v154 offset:16384
	ds_read_b128 v[222:225], v154 offset:18432
	ds_read_b128 v[226:229], v153 offset:20480
	ds_read_b128 v[230:233], v153 offset:22528
	ds_read_b128 v[234:237], v154 offset:20480
	ds_read_b128 v[238:241], v154 offset:22528
	global_load_lds_dwordx4 v[140:141], off
	v_lshl_add_u64 v[242:243], v[140:141], 0, s[0:1]
	s_add_i32 m0, s84, 0x2000
	s_add_i32 s84, s72, s3
	global_load_lds_dwordx4 v[242:243], off
	v_lshl_add_u64 v[242:243], v[140:141], 0, s[12:13]
	s_mov_b32 m0, s84
	s_nop 0
	global_load_lds_dwordx4 v[242:243], off
	v_lshl_add_u64 v[242:243], v[140:141], 0, s[14:15]
	s_add_i32 m0, s84, 0x2000
	s_nop 0
	global_load_lds_dwordx4 v[242:243], off
	s_waitcnt vmcnt(4)
	s_waitcnt lgkmcnt(0)
	s_barrier
	v_mfma_f32_16x16x32_bf16 v[64:67], v[168:171], v[210:213], 0
	v_mfma_f32_16x16x32_bf16 v[64:67], v[174:177], v[218:221], v[64:67]
	v_mfma_f32_16x16x32_bf16 v[60:63], v[178:181], v[210:213], 0
	v_mfma_f32_16x16x32_bf16 v[60:63], v[182:185], v[218:221], v[60:63]
	v_mfma_f32_16x16x32_bf16 v[56:59], v[194:197], v[210:213], 0
	v_mfma_f32_16x16x32_bf16 v[56:59], v[198:201], v[218:221], v[56:59]
	v_mfma_f32_16x16x32_bf16 v[52:55], v[202:205], v[210:213], 0
	v_mfma_f32_16x16x32_bf16 v[52:55], v[206:209], v[218:221], v[52:55]
	v_mfma_f32_16x16x32_bf16 v[36:39], v[202:205], v[214:217], 0
	v_mfma_f32_16x16x32_bf16 v[36:39], v[206:209], v[222:225], v[36:39]
	v_mfma_f32_16x16x32_bf16 v[40:43], v[194:197], v[214:217], 0
	v_mfma_f32_16x16x32_bf16 v[40:43], v[198:201], v[222:225], v[40:43]
	v_mfma_f32_16x16x32_bf16 v[44:47], v[178:181], v[214:217], 0
	v_mfma_f32_16x16x32_bf16 v[44:47], v[182:185], v[222:225], v[44:47]
	v_mfma_f32_16x16x32_bf16 v[48:51], v[168:171], v[214:217], 0
	v_mfma_f32_16x16x32_bf16 v[48:51], v[174:177], v[222:225], v[48:51]
	v_mfma_f32_16x16x32_bf16 v[32:35], v[168:171], v[226:229], 0
	v_mfma_f32_16x16x32_bf16 v[32:35], v[174:177], v[234:237], v[32:35]
	v_mfma_f32_16x16x32_bf16 v[28:31], v[178:181], v[226:229], 0
	v_mfma_f32_16x16x32_bf16 v[28:31], v[182:185], v[234:237], v[28:31]
	v_mfma_f32_16x16x32_bf16 v[24:27], v[194:197], v[226:229], 0
	v_mfma_f32_16x16x32_bf16 v[24:27], v[198:201], v[234:237], v[24:27]
	v_mfma_f32_16x16x32_bf16 v[20:23], v[202:205], v[226:229], 0
	v_mfma_f32_16x16x32_bf16 v[20:23], v[206:209], v[234:237], v[20:23]
	v_mfma_f32_16x16x32_bf16 v[4:7], v[202:205], v[230:233], 0
	v_mfma_f32_16x16x32_bf16 v[4:7], v[206:209], v[238:241], v[4:7]
	v_mfma_f32_16x16x32_bf16 v[8:11], v[194:197], v[230:233], 0
	v_mfma_f32_16x16x32_bf16 v[8:11], v[198:201], v[238:241], v[8:11]
	v_mfma_f32_16x16x32_bf16 v[12:15], v[178:181], v[230:233], 0
	v_mfma_f32_16x16x32_bf16 v[12:15], v[182:185], v[238:241], v[12:15]
	v_mfma_f32_16x16x32_bf16 v[16:19], v[168:171], v[230:233], 0
	v_mfma_f32_16x16x32_bf16 v[16:19], v[174:177], v[238:241], v[16:19]
	s_barrier
	ds_read_b128 v[168:171], v163
	ds_read_b128 v[174:177], v164
	ds_read_b128 v[178:181], v155
	ds_read_b128 v[182:185], v160
	ds_read_b128 v[194:197], v165
	ds_read_b128 v[198:201], v166
	ds_read_b128 v[202:205], v161
	ds_read_b128 v[206:209], v162
	s_mov_b32 m0, s34
	v_lshl_add_u64 v[242:243], s[70:71], 0, v[0:1]
	ds_read_b128 v[210:213], v153 offset:32768
	ds_read_b128 v[214:217], v153 offset:34816
	ds_read_b128 v[218:221], v154 offset:32768
	ds_read_b128 v[222:225], v154 offset:34816
	ds_read_b128 v[226:229], v153 offset:36864
	ds_read_b128 v[230:233], v153 offset:38912
	ds_read_b128 v[234:237], v154 offset:36864
	ds_read_b128 v[238:241], v154 offset:38912
	global_load_lds_dwordx4 v[242:243], off
	v_lshl_add_u64 v[244:245], v[242:243], 0, s[16:17]
	s_mov_b32 m0, s35
	s_nop 0
	global_load_lds_dwordx4 v[244:245], off
	v_lshl_add_u64 v[244:245], v[242:243], 0, s[0:1]
	s_mov_b32 m0, s38
	v_lshl_add_u64 v[242:243], v[242:243], 0, s[18:19]
	global_load_lds_dwordx4 v[244:245], off
	s_mov_b32 m0, s39
	s_nop 0
	global_load_lds_dwordx4 v[242:243], off
	s_waitcnt vmcnt(8)
	s_waitcnt lgkmcnt(0)
	s_barrier
	v_mfma_f32_16x16x32_bf16 v[128:131], v[168:171], v[210:213], v[128:131]
	v_mfma_f32_16x16x32_bf16 v[128:131], v[174:177], v[218:221], v[128:131]
	v_mfma_f32_16x16x32_bf16 v[124:127], v[182:185], v[218:221], v[124:127]
	v_mfma_f32_16x16x32_bf16 v[124:127], v[178:181], v[210:213], v[124:127]
	v_mfma_f32_16x16x32_bf16 v[120:123], v[194:197], v[210:213], v[120:123]
	v_mfma_f32_16x16x32_bf16 v[120:123], v[198:201], v[218:221], v[120:123]
	v_mfma_f32_16x16x32_bf16 v[116:119], v[206:209], v[218:221], v[116:119]
	v_mfma_f32_16x16x32_bf16 v[116:119], v[202:205], v[210:213], v[116:119]
	v_mfma_f32_16x16x32_bf16 v[100:103], v[202:205], v[214:217], v[100:103]
	v_mfma_f32_16x16x32_bf16 v[100:103], v[206:209], v[222:225], v[100:103]
	v_mfma_f32_16x16x32_bf16 v[104:107], v[198:201], v[222:225], v[104:107]
	v_mfma_f32_16x16x32_bf16 v[104:107], v[194:197], v[214:217], v[104:107]
	v_mfma_f32_16x16x32_bf16 v[108:111], v[178:181], v[214:217], v[108:111]
	v_mfma_f32_16x16x32_bf16 v[108:111], v[182:185], v[222:225], v[108:111]
	v_mfma_f32_16x16x32_bf16 v[112:115], v[174:177], v[222:225], v[112:115]
	v_mfma_f32_16x16x32_bf16 v[112:115], v[168:171], v[214:217], v[112:115]
	v_mfma_f32_16x16x32_bf16 v[96:99], v[168:171], v[226:229], v[96:99]
	v_mfma_f32_16x16x32_bf16 v[96:99], v[174:177], v[234:237], v[96:99]
	v_mfma_f32_16x16x32_bf16 v[92:95], v[182:185], v[234:237], v[92:95]
	v_mfma_f32_16x16x32_bf16 v[92:95], v[178:181], v[226:229], v[92:95]
	v_mfma_f32_16x16x32_bf16 v[88:91], v[194:197], v[226:229], v[88:91]
	v_mfma_f32_16x16x32_bf16 v[88:91], v[198:201], v[234:237], v[88:91]
	v_mfma_f32_16x16x32_bf16 v[84:87], v[206:209], v[234:237], v[84:87]
	v_mfma_f32_16x16x32_bf16 v[84:87], v[202:205], v[226:229], v[84:87]
	v_mfma_f32_16x16x32_bf16 v[68:71], v[202:205], v[230:233], v[68:71]
	v_mfma_f32_16x16x32_bf16 v[68:71], v[206:209], v[238:241], v[68:71]
	v_mfma_f32_16x16x32_bf16 v[72:75], v[198:201], v[238:241], v[72:75]
	v_mfma_f32_16x16x32_bf16 v[72:75], v[194:197], v[230:233], v[72:75]
	v_mfma_f32_16x16x32_bf16 v[76:79], v[178:181], v[230:233], v[76:79]
	v_mfma_f32_16x16x32_bf16 v[76:79], v[182:185], v[238:241], v[76:79]
	v_mfma_f32_16x16x32_bf16 v[80:83], v[174:177], v[238:241], v[80:83]
	v_mfma_f32_16x16x32_bf16 v[80:83], v[168:171], v[230:233], v[80:83]
	s_barrier
	s_add_i32 s70, s73, s3
	v_lshl_add_u64 v[242:243], v[140:141], 0, s[22:23]
	s_mov_b32 m0, s70
	ds_read_b128 v[210:213], v153 offset:49152
	ds_read_b128 v[214:217], v153 offset:51200
	ds_read_b128 v[218:221], v154 offset:49152
	ds_read_b128 v[222:225], v154 offset:51200
	ds_read_b128 v[226:229], v153 offset:53248
	ds_read_b128 v[230:233], v153 offset:55296
	ds_read_b128 v[234:237], v154 offset:53248
	ds_read_b128 v[238:241], v154 offset:55296
	global_load_lds_dwordx4 v[242:243], off
	v_lshl_add_u64 v[242:243], v[140:141], 0, s[24:25]
	s_add_i32 m0, s70, 0x2000
	s_add_i32 s70, s77, s3
	global_load_lds_dwordx4 v[242:243], off
	v_lshl_add_u64 v[242:243], v[140:141], 0, s[28:29]
	s_mov_b32 m0, s70
	v_lshl_add_u64 v[140:141], v[140:141], 0, s[36:37]
	global_load_lds_dwordx4 v[242:243], off
	s_add_i32 m0, s70, 0x2000
	s_nop 0
	global_load_lds_dwordx4 v[140:141], off
	s_waitcnt vmcnt(4)
	s_waitcnt lgkmcnt(0)
	s_barrier
	v_mfma_f32_16x16x32_bf16 v[64:67], v[168:171], v[210:213], v[64:67]
	v_mfma_f32_16x16x32_bf16 v[64:67], v[174:177], v[218:221], v[64:67]
	v_mfma_f32_16x16x32_bf16 v[60:63], v[182:185], v[218:221], v[60:63]
	v_mfma_f32_16x16x32_bf16 v[60:63], v[178:181], v[210:213], v[60:63]
	v_mfma_f32_16x16x32_bf16 v[56:59], v[194:197], v[210:213], v[56:59]
	v_mfma_f32_16x16x32_bf16 v[56:59], v[198:201], v[218:221], v[56:59]
	v_mfma_f32_16x16x32_bf16 v[52:55], v[206:209], v[218:221], v[52:55]
	v_mfma_f32_16x16x32_bf16 v[52:55], v[202:205], v[210:213], v[52:55]
	v_mfma_f32_16x16x32_bf16 v[36:39], v[202:205], v[214:217], v[36:39]
	v_mfma_f32_16x16x32_bf16 v[36:39], v[206:209], v[222:225], v[36:39]
	v_mfma_f32_16x16x32_bf16 v[40:43], v[198:201], v[222:225], v[40:43]
	v_mfma_f32_16x16x32_bf16 v[40:43], v[194:197], v[214:217], v[40:43]
	v_mfma_f32_16x16x32_bf16 v[44:47], v[178:181], v[214:217], v[44:47]
	v_mfma_f32_16x16x32_bf16 v[44:47], v[182:185], v[222:225], v[44:47]
	v_mfma_f32_16x16x32_bf16 v[48:51], v[174:177], v[222:225], v[48:51]
	v_mfma_f32_16x16x32_bf16 v[48:51], v[168:171], v[214:217], v[48:51]
	v_mfma_f32_16x16x32_bf16 v[32:35], v[168:171], v[226:229], v[32:35]
	v_mfma_f32_16x16x32_bf16 v[32:35], v[174:177], v[234:237], v[32:35]
	v_mfma_f32_16x16x32_bf16 v[28:31], v[182:185], v[234:237], v[28:31]
	v_mfma_f32_16x16x32_bf16 v[28:31], v[178:181], v[226:229], v[28:31]
	v_mfma_f32_16x16x32_bf16 v[24:27], v[194:197], v[226:229], v[24:27]
	v_mfma_f32_16x16x32_bf16 v[24:27], v[198:201], v[234:237], v[24:27]
	v_mfma_f32_16x16x32_bf16 v[20:23], v[206:209], v[234:237], v[20:23]
	v_mfma_f32_16x16x32_bf16 v[20:23], v[202:205], v[226:229], v[20:23]
	v_mfma_f32_16x16x32_bf16 v[4:7], v[202:205], v[230:233], v[4:7]
	v_mfma_f32_16x16x32_bf16 v[4:7], v[206:209], v[238:241], v[4:7]
	v_mfma_f32_16x16x32_bf16 v[8:11], v[198:201], v[238:241], v[8:11]
	v_mfma_f32_16x16x32_bf16 v[8:11], v[194:197], v[230:233], v[8:11]
	v_mfma_f32_16x16x32_bf16 v[12:15], v[178:181], v[230:233], v[12:15]
	v_mfma_f32_16x16x32_bf16 v[12:15], v[182:185], v[238:241], v[12:15]
	v_mfma_f32_16x16x32_bf16 v[16:19], v[174:177], v[238:241], v[16:19]
	v_mfma_f32_16x16x32_bf16 v[16:19], v[168:171], v[230:233], v[16:19]
	s_barrier
	s_add_i32 s83, s83, 2
	s_add_u32 s68, s68, 0x100
	s_addc_u32 s69, s69, 0
	s_cmp_gt_u32 s83, 13
.LBB0_1135:
	ds_read_b128 v[168:171], v145
	ds_read_b128 v[174:177], v146
	ds_read_b128 v[178:181], v147
	ds_read_b128 v[182:185], v148
	ds_read_b128 v[194:197], v149
	ds_read_b128 v[198:201], v150
	ds_read_b128 v[202:205], v151
	ds_read_b128 v[206:209], v152
	s_add_u32 s70, s26, s68
	s_addc_u32 s71, s27, s69
	s_add_u32 s70, s70, 0x100
	s_addc_u32 s71, s71, 0
	s_add_u32 s84, s81, s68
	s_addc_u32 s85, s82, s69
	s_cmpk_eq_i32 s68, 0x700
	s_cselect_b32 s85, s59, s85
	s_cselect_b32 s84, s80, s84
	s_cselect_b32 s71, s57, s71
	s_cselect_b32 s70, s79, s70
	v_lshl_add_u64 v[140:141], v[138:139], 0, s[68:69]
	v_lshl_add_u64 v[242:243], v[140:141], 0, s[22:23]
	s_add_i32 m0, s34, 0x8000
	s_mov_b64 s[86:87], 0x20080
	ds_read_b128 v[210:213], v153
	ds_read_b128 v[214:217], v153 offset:2048
	ds_read_b128 v[218:221], v154
	ds_read_b128 v[222:225], v154 offset:2048
	ds_read_b128 v[226:229], v153 offset:4096
	ds_read_b128 v[230:233], v153 offset:6144
	ds_read_b128 v[234:237], v154 offset:4096
	ds_read_b128 v[238:241], v154 offset:6144
	global_load_lds_dwordx4 v[242:243], off
	v_lshl_add_u64 v[242:243], v[140:141], 0, s[86:87]
	s_add_i32 m0, s34, 0xa000
	s_mov_b64 s[86:87], 0x60080
	global_load_lds_dwordx4 v[242:243], off
	v_lshl_add_u64 v[242:243], v[140:141], 0, s[24:25]
	s_add_i32 m0, s34, 0xc000
	v_lshl_add_u64 v[140:141], v[140:141], 0, s[86:87]
	global_load_lds_dwordx4 v[242:243], off
	s_add_i32 m0, s34, 0xe000
	s_nop 0
	global_load_lds_dwordx4 v[140:141], off
	s_waitcnt vmcnt(8)
	s_waitcnt lgkmcnt(0)
	s_barrier
	v_mfma_f32_16x16x32_bf16 v[128:131], v[168:171], v[210:213], v[128:131]
	v_mfma_f32_16x16x32_bf16 v[128:131], v[174:177], v[218:221], v[128:131]
	v_mfma_f32_16x16x32_bf16 v[124:127], v[182:185], v[218:221], v[124:127]
	v_mfma_f32_16x16x32_bf16 v[124:127], v[178:181], v[210:213], v[124:127]
	v_mfma_f32_16x16x32_bf16 v[120:123], v[194:197], v[210:213], v[120:123]
	v_mfma_f32_16x16x32_bf16 v[120:123], v[198:201], v[218:221], v[120:123]
	v_mfma_f32_16x16x32_bf16 v[116:119], v[206:209], v[218:221], v[116:119]
	v_mfma_f32_16x16x32_bf16 v[116:119], v[202:205], v[210:213], v[116:119]
	v_mfma_f32_16x16x32_bf16 v[100:103], v[202:205], v[214:217], v[100:103]
	v_mfma_f32_16x16x32_bf16 v[100:103], v[206:209], v[222:225], v[100:103]
	v_mfma_f32_16x16x32_bf16 v[104:107], v[198:201], v[222:225], v[104:107]
	v_mfma_f32_16x16x32_bf16 v[104:107], v[194:197], v[214:217], v[104:107]
	v_mfma_f32_16x16x32_bf16 v[108:111], v[178:181], v[214:217], v[108:111]
	v_mfma_f32_16x16x32_bf16 v[108:111], v[182:185], v[222:225], v[108:111]
	v_mfma_f32_16x16x32_bf16 v[112:115], v[174:177], v[222:225], v[112:115]
	v_mfma_f32_16x16x32_bf16 v[112:115], v[168:171], v[214:217], v[112:115]
	v_mfma_f32_16x16x32_bf16 v[96:99], v[168:171], v[226:229], v[96:99]
	v_mfma_f32_16x16x32_bf16 v[96:99], v[174:177], v[234:237], v[96:99]
	v_mfma_f32_16x16x32_bf16 v[92:95], v[182:185], v[234:237], v[92:95]
	v_mfma_f32_16x16x32_bf16 v[92:95], v[178:181], v[226:229], v[92:95]
	v_mfma_f32_16x16x32_bf16 v[88:91], v[194:197], v[226:229], v[88:91]
	v_mfma_f32_16x16x32_bf16 v[88:91], v[198:201], v[234:237], v[88:91]
	v_mfma_f32_16x16x32_bf16 v[84:87], v[206:209], v[234:237], v[84:87]
	v_mfma_f32_16x16x32_bf16 v[84:87], v[202:205], v[226:229], v[84:87]
	v_mfma_f32_16x16x32_bf16 v[68:71], v[202:205], v[230:233], v[68:71]
	v_mfma_f32_16x16x32_bf16 v[68:71], v[206:209], v[238:241], v[68:71]
	v_mfma_f32_16x16x32_bf16 v[72:75], v[198:201], v[238:241], v[72:75]
	v_mfma_f32_16x16x32_bf16 v[72:75], v[194:197], v[230:233], v[72:75]
	v_mfma_f32_16x16x32_bf16 v[76:79], v[178:181], v[230:233], v[76:79]
	v_mfma_f32_16x16x32_bf16 v[76:79], v[182:185], v[238:241], v[76:79]
	v_mfma_f32_16x16x32_bf16 v[80:83], v[174:177], v[238:241], v[80:83]
	v_mfma_f32_16x16x32_bf16 v[80:83], v[168:171], v[230:233], v[80:83]
	s_barrier
	v_lshl_add_u64 v[140:141], s[84:85], 0, v[158:159]
	s_add_i32 s84, s67, s3
	s_mov_b32 m0, s84
	ds_read_b128 v[210:213], v153 offset:16384
	ds_read_b128 v[214:217], v153 offset:18432
	ds_read_b128 v[218:221], v154 offset:16384
	ds_read_b128 v[222:225], v154 offset:18432
	ds_read_b128 v[226:229], v153 offset:20480
	ds_read_b128 v[230:233], v153 offset:22528
	ds_read_b128 v[234:237], v154 offset:20480
	ds_read_b128 v[238:241], v154 offset:22528
	global_load_lds_dwordx4 v[140:141], off
	v_lshl_add_u64 v[242:243], v[140:141], 0, s[0:1]
	s_add_i32 m0, s84, 0x2000
	s_add_i32 s84, s72, s3
	global_load_lds_dwordx4 v[242:243], off
	v_lshl_add_u64 v[242:243], v[140:141], 0, s[12:13]
	s_mov_b32 m0, s84
	s_nop 0
	global_load_lds_dwordx4 v[242:243], off
	v_lshl_add_u64 v[242:243], v[140:141], 0, s[14:15]
	s_add_i32 m0, s84, 0x2000
	s_nop 0
	global_load_lds_dwordx4 v[242:243], off
	s_waitcnt vmcnt(4)
	s_waitcnt lgkmcnt(0)
	s_barrier
	v_mfma_f32_16x16x32_bf16 v[64:67], v[168:171], v[210:213], v[64:67]
	v_mfma_f32_16x16x32_bf16 v[64:67], v[174:177], v[218:221], v[64:67]
	v_mfma_f32_16x16x32_bf16 v[60:63], v[182:185], v[218:221], v[60:63]
	v_mfma_f32_16x16x32_bf16 v[60:63], v[178:181], v[210:213], v[60:63]
	v_mfma_f32_16x16x32_bf16 v[56:59], v[194:197], v[210:213], v[56:59]
	v_mfma_f32_16x16x32_bf16 v[56:59], v[198:201], v[218:221], v[56:59]
	v_mfma_f32_16x16x32_bf16 v[52:55], v[206:209], v[218:221], v[52:55]
	v_mfma_f32_16x16x32_bf16 v[52:55], v[202:205], v[210:213], v[52:55]
	v_mfma_f32_16x16x32_bf16 v[36:39], v[202:205], v[214:217], v[36:39]
	v_mfma_f32_16x16x32_bf16 v[36:39], v[206:209], v[222:225], v[36:39]
	v_mfma_f32_16x16x32_bf16 v[40:43], v[198:201], v[222:225], v[40:43]
	v_mfma_f32_16x16x32_bf16 v[40:43], v[194:197], v[214:217], v[40:43]
	v_mfma_f32_16x16x32_bf16 v[44:47], v[178:181], v[214:217], v[44:47]
	v_mfma_f32_16x16x32_bf16 v[44:47], v[182:185], v[222:225], v[44:47]
	v_mfma_f32_16x16x32_bf16 v[48:51], v[174:177], v[222:225], v[48:51]
	v_mfma_f32_16x16x32_bf16 v[48:51], v[168:171], v[214:217], v[48:51]
	v_mfma_f32_16x16x32_bf16 v[32:35], v[168:171], v[226:229], v[32:35]
	v_mfma_f32_16x16x32_bf16 v[32:35], v[174:177], v[234:237], v[32:35]
	v_mfma_f32_16x16x32_bf16 v[28:31], v[182:185], v[234:237], v[28:31]
	v_mfma_f32_16x16x32_bf16 v[28:31], v[178:181], v[226:229], v[28:31]
	v_mfma_f32_16x16x32_bf16 v[24:27], v[194:197], v[226:229], v[24:27]
	v_mfma_f32_16x16x32_bf16 v[24:27], v[198:201], v[234:237], v[24:27]
	v_mfma_f32_16x16x32_bf16 v[20:23], v[206:209], v[234:237], v[20:23]
	v_mfma_f32_16x16x32_bf16 v[20:23], v[202:205], v[226:229], v[20:23]
	v_mfma_f32_16x16x32_bf16 v[4:7], v[202:205], v[230:233], v[4:7]
	v_mfma_f32_16x16x32_bf16 v[4:7], v[206:209], v[238:241], v[4:7]
	v_mfma_f32_16x16x32_bf16 v[8:11], v[198:201], v[238:241], v[8:11]
	v_mfma_f32_16x16x32_bf16 v[8:11], v[194:197], v[230:233], v[8:11]
	v_mfma_f32_16x16x32_bf16 v[12:15], v[178:181], v[230:233], v[12:15]
	v_mfma_f32_16x16x32_bf16 v[12:15], v[182:185], v[238:241], v[12:15]
	v_mfma_f32_16x16x32_bf16 v[16:19], v[174:177], v[238:241], v[16:19]
	v_mfma_f32_16x16x32_bf16 v[16:19], v[168:171], v[230:233], v[16:19]
	s_barrier
	ds_read_b128 v[168:171], v163
	ds_read_b128 v[174:177], v164
	ds_read_b128 v[178:181], v155
	ds_read_b128 v[182:185], v160
	ds_read_b128 v[194:197], v165
	ds_read_b128 v[198:201], v166
	ds_read_b128 v[202:205], v161
	ds_read_b128 v[206:209], v162
	s_mov_b32 m0, s34
	v_lshl_add_u64 v[242:243], s[70:71], 0, v[0:1]
	ds_read_b128 v[210:213], v153 offset:32768
	ds_read_b128 v[214:217], v153 offset:34816
	ds_read_b128 v[218:221], v154 offset:32768
	ds_read_b128 v[222:225], v154 offset:34816
	ds_read_b128 v[226:229], v153 offset:36864
	ds_read_b128 v[230:233], v153 offset:38912
	ds_read_b128 v[234:237], v154 offset:36864
	ds_read_b128 v[238:241], v154 offset:38912
	global_load_lds_dwordx4 v[242:243], off
	v_lshl_add_u64 v[244:245], v[242:243], 0, s[16:17]
	s_mov_b32 m0, s35
	s_nop 0
	global_load_lds_dwordx4 v[244:245], off
	v_lshl_add_u64 v[244:245], v[242:243], 0, s[0:1]
	s_mov_b32 m0, s38
	v_lshl_add_u64 v[242:243], v[242:243], 0, s[18:19]
	global_load_lds_dwordx4 v[244:245], off
	s_mov_b32 m0, s39
	s_nop 0
	global_load_lds_dwordx4 v[242:243], off
	s_waitcnt vmcnt(8)
	s_waitcnt lgkmcnt(0)
	s_barrier
	v_mfma_f32_16x16x32_bf16 v[128:131], v[168:171], v[210:213], v[128:131]
	v_mfma_f32_16x16x32_bf16 v[128:131], v[174:177], v[218:221], v[128:131]
	v_mfma_f32_16x16x32_bf16 v[124:127], v[182:185], v[218:221], v[124:127]
	v_mfma_f32_16x16x32_bf16 v[124:127], v[178:181], v[210:213], v[124:127]
	v_mfma_f32_16x16x32_bf16 v[120:123], v[194:197], v[210:213], v[120:123]
	v_mfma_f32_16x16x32_bf16 v[120:123], v[198:201], v[218:221], v[120:123]
	v_mfma_f32_16x16x32_bf16 v[116:119], v[206:209], v[218:221], v[116:119]
	v_mfma_f32_16x16x32_bf16 v[116:119], v[202:205], v[210:213], v[116:119]
	v_mfma_f32_16x16x32_bf16 v[100:103], v[202:205], v[214:217], v[100:103]
	v_mfma_f32_16x16x32_bf16 v[100:103], v[206:209], v[222:225], v[100:103]
	v_mfma_f32_16x16x32_bf16 v[104:107], v[198:201], v[222:225], v[104:107]
	v_mfma_f32_16x16x32_bf16 v[104:107], v[194:197], v[214:217], v[104:107]
	v_mfma_f32_16x16x32_bf16 v[108:111], v[178:181], v[214:217], v[108:111]
	v_mfma_f32_16x16x32_bf16 v[108:111], v[182:185], v[222:225], v[108:111]
	v_mfma_f32_16x16x32_bf16 v[112:115], v[174:177], v[222:225], v[112:115]
	v_mfma_f32_16x16x32_bf16 v[112:115], v[168:171], v[214:217], v[112:115]
	v_mfma_f32_16x16x32_bf16 v[96:99], v[168:171], v[226:229], v[96:99]
	v_mfma_f32_16x16x32_bf16 v[96:99], v[174:177], v[234:237], v[96:99]
	v_mfma_f32_16x16x32_bf16 v[92:95], v[182:185], v[234:237], v[92:95]
	v_mfma_f32_16x16x32_bf16 v[92:95], v[178:181], v[226:229], v[92:95]
	v_mfma_f32_16x16x32_bf16 v[88:91], v[194:197], v[226:229], v[88:91]
	v_mfma_f32_16x16x32_bf16 v[88:91], v[198:201], v[234:237], v[88:91]
	v_mfma_f32_16x16x32_bf16 v[84:87], v[206:209], v[234:237], v[84:87]
	v_mfma_f32_16x16x32_bf16 v[84:87], v[202:205], v[226:229], v[84:87]
	v_mfma_f32_16x16x32_bf16 v[68:71], v[202:205], v[230:233], v[68:71]
	v_mfma_f32_16x16x32_bf16 v[68:71], v[206:209], v[238:241], v[68:71]
	v_mfma_f32_16x16x32_bf16 v[72:75], v[198:201], v[238:241], v[72:75]
	v_mfma_f32_16x16x32_bf16 v[72:75], v[194:197], v[230:233], v[72:75]
	v_mfma_f32_16x16x32_bf16 v[76:79], v[178:181], v[230:233], v[76:79]
	v_mfma_f32_16x16x32_bf16 v[76:79], v[182:185], v[238:241], v[76:79]
	v_mfma_f32_16x16x32_bf16 v[80:83], v[174:177], v[238:241], v[80:83]
	v_mfma_f32_16x16x32_bf16 v[80:83], v[168:171], v[230:233], v[80:83]
	s_barrier
	s_add_i32 s70, s73, s3
	v_lshl_add_u64 v[242:243], v[140:141], 0, s[22:23]
	s_mov_b32 m0, s70
	ds_read_b128 v[210:213], v153 offset:49152
	ds_read_b128 v[214:217], v153 offset:51200
	ds_read_b128 v[218:221], v154 offset:49152
	ds_read_b128 v[222:225], v154 offset:51200
	ds_read_b128 v[226:229], v153 offset:53248
	ds_read_b128 v[230:233], v153 offset:55296
	ds_read_b128 v[234:237], v154 offset:53248
	ds_read_b128 v[238:241], v154 offset:55296
	global_load_lds_dwordx4 v[242:243], off
	v_lshl_add_u64 v[242:243], v[140:141], 0, s[24:25]
	s_add_i32 m0, s70, 0x2000
	s_add_i32 s70, s77, s3
	global_load_lds_dwordx4 v[242:243], off
	v_lshl_add_u64 v[242:243], v[140:141], 0, s[28:29]
	s_mov_b32 m0, s70
	v_lshl_add_u64 v[140:141], v[140:141], 0, s[36:37]
	global_load_lds_dwordx4 v[242:243], off
	s_add_i32 m0, s70, 0x2000
	s_nop 0
	global_load_lds_dwordx4 v[140:141], off
	s_waitcnt vmcnt(4)
	s_waitcnt lgkmcnt(0)
	s_barrier
	v_mfma_f32_16x16x32_bf16 v[64:67], v[168:171], v[210:213], v[64:67]
	v_mfma_f32_16x16x32_bf16 v[64:67], v[174:177], v[218:221], v[64:67]
	v_mfma_f32_16x16x32_bf16 v[60:63], v[182:185], v[218:221], v[60:63]
	v_mfma_f32_16x16x32_bf16 v[60:63], v[178:181], v[210:213], v[60:63]
	v_mfma_f32_16x16x32_bf16 v[56:59], v[194:197], v[210:213], v[56:59]
	v_mfma_f32_16x16x32_bf16 v[56:59], v[198:201], v[218:221], v[56:59]
	v_mfma_f32_16x16x32_bf16 v[52:55], v[206:209], v[218:221], v[52:55]
	v_mfma_f32_16x16x32_bf16 v[52:55], v[202:205], v[210:213], v[52:55]
	v_mfma_f32_16x16x32_bf16 v[36:39], v[202:205], v[214:217], v[36:39]
	v_mfma_f32_16x16x32_bf16 v[36:39], v[206:209], v[222:225], v[36:39]
	v_mfma_f32_16x16x32_bf16 v[40:43], v[198:201], v[222:225], v[40:43]
	v_mfma_f32_16x16x32_bf16 v[40:43], v[194:197], v[214:217], v[40:43]
	v_mfma_f32_16x16x32_bf16 v[44:47], v[178:181], v[214:217], v[44:47]
	v_mfma_f32_16x16x32_bf16 v[44:47], v[182:185], v[222:225], v[44:47]
	v_mfma_f32_16x16x32_bf16 v[48:51], v[174:177], v[222:225], v[48:51]
	v_mfma_f32_16x16x32_bf16 v[48:51], v[168:171], v[214:217], v[48:51]
	v_mfma_f32_16x16x32_bf16 v[32:35], v[168:171], v[226:229], v[32:35]
	v_mfma_f32_16x16x32_bf16 v[32:35], v[174:177], v[234:237], v[32:35]
	v_mfma_f32_16x16x32_bf16 v[28:31], v[182:185], v[234:237], v[28:31]
	v_mfma_f32_16x16x32_bf16 v[28:31], v[178:181], v[226:229], v[28:31]
	v_mfma_f32_16x16x32_bf16 v[24:27], v[194:197], v[226:229], v[24:27]
	v_mfma_f32_16x16x32_bf16 v[24:27], v[198:201], v[234:237], v[24:27]
	v_mfma_f32_16x16x32_bf16 v[20:23], v[206:209], v[234:237], v[20:23]
	v_mfma_f32_16x16x32_bf16 v[20:23], v[202:205], v[226:229], v[20:23]
	v_mfma_f32_16x16x32_bf16 v[4:7], v[202:205], v[230:233], v[4:7]
	v_mfma_f32_16x16x32_bf16 v[4:7], v[206:209], v[238:241], v[4:7]
	v_mfma_f32_16x16x32_bf16 v[8:11], v[198:201], v[238:241], v[8:11]
	v_mfma_f32_16x16x32_bf16 v[8:11], v[194:197], v[230:233], v[8:11]
	v_mfma_f32_16x16x32_bf16 v[12:15], v[178:181], v[230:233], v[12:15]
	v_mfma_f32_16x16x32_bf16 v[12:15], v[182:185], v[238:241], v[12:15]
	v_mfma_f32_16x16x32_bf16 v[16:19], v[174:177], v[238:241], v[16:19]
	v_mfma_f32_16x16x32_bf16 v[16:19], v[168:171], v[230:233], v[16:19]
	s_barrier
	s_add_i32 s83, s83, 2
	s_add_u32 s68, s68, 0x100
	s_addc_u32 s69, s69, 0
	s_cmp_gt_u32 s83, 13
	s_cbranch_scc0 .LBB0_1135
	s_and_b64 vcc, exec, s[40:41]
	s_cbranch_vccz .LBB0_1138
	s_barrier

.LBB0_1371:
	v_add_u32_e32 v147, s64, v143
	v_add_u32_e32 v152, s64, v144
	ds_read_b128 v[148:151], v147
	ds_read_b128 v[152:155], v152
	v_add_u32_e32 v147, s65, v143
	v_add_u32_e32 v162, s65, v144
	s_add_u32 s58, s18, s56
	ds_read_b128 v[158:161], v147
	ds_read_b128 v[162:165], v162
	v_add_u32_e32 v147, s66, v143
	s_addc_u32 s59, s19, s57
	v_add_u32_e32 v166, s66, v144
	ds_read_b128 v[170:173], v147
	ds_read_b128 v[174:177], v166
	v_add_u32_e32 v147, s67, v143
	s_add_u32 s58, s58, 0x100
	v_add_u32_e32 v166, s67, v144
	ds_read_b128 v[178:181], v147
	ds_read_b128 v[182:185], v166
	s_addc_u32 s59, s59, 0
	s_add_u32 s78, s53, s56
	s_addc_u32 s79, s72, s57
	s_cmpk_eq_i32 s56, 0x1f00
	s_cselect_b32 s79, s49, s79
	s_cselect_b32 s78, s76, s78
	s_cselect_b32 s59, s51, s59
	s_cselect_b32 s58, s73, s58
	v_lshl_add_u64 v[166:167], v[140:141], 0, s[56:57]
	v_lshl_add_u64 v[218:219], v[166:167], 0, s[24:25]
	s_add_i32 m0, s35, 0x8000
	ds_read_b128 v[186:189], v145
	ds_read_b128 v[190:193], v145 offset:2048
	ds_read_b128 v[194:197], v146
	ds_read_b128 v[198:201], v146 offset:2048
	ds_read_b128 v[202:205], v145 offset:4096
	ds_read_b128 v[206:209], v145 offset:6144
	ds_read_b128 v[210:213], v146 offset:4096
	ds_read_b128 v[214:217], v146 offset:6144
	global_load_lds_dwordx4 v[218:219], off
	v_lshl_add_u64 v[218:219], v[166:167], 0, s[44:45]
	s_add_i32 m0, s35, 0xa000
	s_nop 0
	global_load_lds_dwordx4 v[218:219], off
	v_lshl_add_u64 v[218:219], v[166:167], 0, s[28:29]
	s_add_i32 m0, s35, 0xc000
	v_lshl_add_u64 v[166:167], v[166:167], 0, s[46:47]
	global_load_lds_dwordx4 v[218:219], off
	s_add_i32 m0, s35, 0xe000
	s_nop 0
	global_load_lds_dwordx4 v[166:167], off
	s_waitcnt vmcnt(8)
	s_waitcnt lgkmcnt(0)
	s_barrier
	v_mfma_f32_16x16x32_bf16 v[128:131], v[148:151], v[186:189], v[128:131]
	v_mfma_f32_16x16x32_bf16 v[128:131], v[152:155], v[194:197], v[128:131]
	v_mfma_f32_16x16x32_bf16 v[124:127], v[162:165], v[194:197], v[124:127]
	v_mfma_f32_16x16x32_bf16 v[124:127], v[158:161], v[186:189], v[124:127]
	v_mfma_f32_16x16x32_bf16 v[120:123], v[170:173], v[186:189], v[120:123]
	v_mfma_f32_16x16x32_bf16 v[120:123], v[174:177], v[194:197], v[120:123]
	v_mfma_f32_16x16x32_bf16 v[116:119], v[182:185], v[194:197], v[116:119]
	v_mfma_f32_16x16x32_bf16 v[116:119], v[178:181], v[186:189], v[116:119]
	v_mfma_f32_16x16x32_bf16 v[100:103], v[178:181], v[190:193], v[100:103]
	v_mfma_f32_16x16x32_bf16 v[100:103], v[182:185], v[198:201], v[100:103]
	v_mfma_f32_16x16x32_bf16 v[104:107], v[174:177], v[198:201], v[104:107]
	v_mfma_f32_16x16x32_bf16 v[104:107], v[170:173], v[190:193], v[104:107]
	v_mfma_f32_16x16x32_bf16 v[108:111], v[158:161], v[190:193], v[108:111]
	v_mfma_f32_16x16x32_bf16 v[108:111], v[162:165], v[198:201], v[108:111]
	v_mfma_f32_16x16x32_bf16 v[112:115], v[152:155], v[198:201], v[112:115]
	v_mfma_f32_16x16x32_bf16 v[112:115], v[148:151], v[190:193], v[112:115]
	v_mfma_f32_16x16x32_bf16 v[96:99], v[148:151], v[202:205], v[96:99]
	v_mfma_f32_16x16x32_bf16 v[96:99], v[152:155], v[210:213], v[96:99]
	v_mfma_f32_16x16x32_bf16 v[92:95], v[162:165], v[210:213], v[92:95]
	v_mfma_f32_16x16x32_bf16 v[92:95], v[158:161], v[202:205], v[92:95]
	v_mfma_f32_16x16x32_bf16 v[88:91], v[170:173], v[202:205], v[88:91]
	v_mfma_f32_16x16x32_bf16 v[88:91], v[174:177], v[210:213], v[88:91]
	v_mfma_f32_16x16x32_bf16 v[84:87], v[182:185], v[210:213], v[84:87]
	v_mfma_f32_16x16x32_bf16 v[84:87], v[178:181], v[202:205], v[84:87]
	v_mfma_f32_16x16x32_bf16 v[68:71], v[178:181], v[206:209], v[68:71]
	v_mfma_f32_16x16x32_bf16 v[68:71], v[182:185], v[214:217], v[68:71]
	v_mfma_f32_16x16x32_bf16 v[72:75], v[174:177], v[214:217], v[72:75]
	v_mfma_f32_16x16x32_bf16 v[72:75], v[170:173], v[206:209], v[72:75]
	v_mfma_f32_16x16x32_bf16 v[76:79], v[158:161], v[206:209], v[76:79]
	v_mfma_f32_16x16x32_bf16 v[76:79], v[162:165], v[214:217], v[76:79]
	v_mfma_f32_16x16x32_bf16 v[80:83], v[152:155], v[214:217], v[80:83]
	v_mfma_f32_16x16x32_bf16 v[80:83], v[148:151], v[206:209], v[80:83]
	s_barrier
	v_lshl_add_u64 v[166:167], s[78:79], 0, v[132:133]
	s_add_i32 s78, s64, s34
	s_mov_b32 m0, s78
	ds_read_b128 v[186:189], v145 offset:16384
	ds_read_b128 v[190:193], v145 offset:18432
	ds_read_b128 v[194:197], v146 offset:16384
	ds_read_b128 v[198:201], v146 offset:18432
	ds_read_b128 v[202:205], v145 offset:20480
	ds_read_b128 v[206:209], v145 offset:22528
	ds_read_b128 v[210:213], v146 offset:20480
	ds_read_b128 v[214:217], v146 offset:22528
	global_load_lds_dwordx4 v[166:167], off
	v_lshl_add_u64 v[218:219], v[166:167], 0, s[10:11]
	s_add_i32 m0, s78, 0x2000
	s_add_i32 s78, s66, s34
	global_load_lds_dwordx4 v[218:219], off
	v_lshl_add_u64 v[218:219], v[166:167], 0, s[14:15]
	s_mov_b32 m0, s78
	s_nop 0
	global_load_lds_dwordx4 v[218:219], off
	v_lshl_add_u64 v[218:219], v[166:167], 0, s[16:17]
	s_add_i32 m0, s78, 0x2000
	s_nop 0
	global_load_lds_dwordx4 v[218:219], off
	s_waitcnt vmcnt(4)
	s_waitcnt lgkmcnt(0)
	s_barrier
	v_mfma_f32_16x16x32_bf16 v[64:67], v[148:151], v[186:189], v[64:67]
	v_mfma_f32_16x16x32_bf16 v[64:67], v[152:155], v[194:197], v[64:67]
	v_mfma_f32_16x16x32_bf16 v[60:63], v[162:165], v[194:197], v[60:63]
	v_mfma_f32_16x16x32_bf16 v[60:63], v[158:161], v[186:189], v[60:63]
	v_mfma_f32_16x16x32_bf16 v[56:59], v[170:173], v[186:189], v[56:59]
	v_mfma_f32_16x16x32_bf16 v[56:59], v[174:177], v[194:197], v[56:59]
	v_mfma_f32_16x16x32_bf16 v[52:55], v[182:185], v[194:197], v[52:55]
	v_mfma_f32_16x16x32_bf16 v[52:55], v[178:181], v[186:189], v[52:55]
	v_mfma_f32_16x16x32_bf16 v[36:39], v[178:181], v[190:193], v[36:39]
	v_mfma_f32_16x16x32_bf16 v[36:39], v[182:185], v[198:201], v[36:39]
	v_mfma_f32_16x16x32_bf16 v[40:43], v[174:177], v[198:201], v[40:43]
	v_mfma_f32_16x16x32_bf16 v[40:43], v[170:173], v[190:193], v[40:43]
	v_mfma_f32_16x16x32_bf16 v[44:47], v[158:161], v[190:193], v[44:47]
	v_mfma_f32_16x16x32_bf16 v[44:47], v[162:165], v[198:201], v[44:47]
	v_mfma_f32_16x16x32_bf16 v[48:51], v[152:155], v[198:201], v[48:51]
	v_mfma_f32_16x16x32_bf16 v[48:51], v[148:151], v[190:193], v[48:51]
	v_mfma_f32_16x16x32_bf16 v[32:35], v[148:151], v[202:205], v[32:35]
	v_mfma_f32_16x16x32_bf16 v[32:35], v[152:155], v[210:213], v[32:35]
	v_mfma_f32_16x16x32_bf16 v[28:31], v[162:165], v[210:213], v[28:31]
	v_mfma_f32_16x16x32_bf16 v[28:31], v[158:161], v[202:205], v[28:31]
	v_mfma_f32_16x16x32_bf16 v[24:27], v[170:173], v[202:205], v[24:27]
	v_mfma_f32_16x16x32_bf16 v[24:27], v[174:177], v[210:213], v[24:27]
	v_mfma_f32_16x16x32_bf16 v[20:23], v[182:185], v[210:213], v[20:23]
	v_mfma_f32_16x16x32_bf16 v[20:23], v[178:181], v[202:205], v[20:23]
	v_mfma_f32_16x16x32_bf16 v[4:7], v[178:181], v[206:209], v[4:7]
	v_mfma_f32_16x16x32_bf16 v[4:7], v[182:185], v[214:217], v[4:7]
	v_mfma_f32_16x16x32_bf16 v[8:11], v[174:177], v[214:217], v[8:11]
	v_mfma_f32_16x16x32_bf16 v[8:11], v[170:173], v[206:209], v[8:11]
	v_mfma_f32_16x16x32_bf16 v[12:15], v[158:161], v[206:209], v[12:15]
	v_mfma_f32_16x16x32_bf16 v[12:15], v[162:165], v[214:217], v[12:15]
	v_mfma_f32_16x16x32_bf16 v[16:19], v[152:155], v[214:217], v[16:19]
	v_mfma_f32_16x16x32_bf16 v[16:19], v[148:151], v[206:209], v[16:19]
	s_barrier
	v_add_u32_e32 v147, s70, v143
	v_add_u32_e32 v152, s70, v144
	ds_read_b128 v[148:151], v147
	ds_read_b128 v[152:155], v152
	v_add_u32_e32 v147, s68, v143
	v_add_u32_e32 v162, s68, v144
	ds_read_b128 v[158:161], v147
	ds_read_b128 v[162:165], v162
	v_add_u32_e32 v147, s71, v143
	v_add_u32_e32 v169, s71, v144
	ds_read_b128 v[170:173], v147
	ds_read_b128 v[174:177], v169
	v_add_u32_e32 v147, s69, v143
	v_add_u32_e32 v169, s69, v144
	ds_read_b128 v[178:181], v147
	ds_read_b128 v[182:185], v169
	s_mov_b32 m0, s35
	v_lshl_add_u64 v[218:219], s[58:59], 0, v[0:1]
	ds_read_b128 v[186:189], v145 offset:32768
	ds_read_b128 v[190:193], v145 offset:34816
	ds_read_b128 v[194:197], v146 offset:32768
	ds_read_b128 v[198:201], v146 offset:34816
	ds_read_b128 v[202:205], v145 offset:36864
	ds_read_b128 v[206:209], v145 offset:38912
	ds_read_b128 v[210:213], v146 offset:36864
	ds_read_b128 v[214:217], v146 offset:38912
	global_load_lds_dwordx4 v[218:219], off
	v_lshl_add_u64 v[220:221], v[218:219], 0, s[20:21]
	s_mov_b32 m0, s39
	s_nop 0
	global_load_lds_dwordx4 v[220:221], off
	v_lshl_add_u64 v[220:221], v[218:219], 0, s[10:11]
	s_mov_b32 m0, s60
	v_lshl_add_u64 v[218:219], v[218:219], 0, s[22:23]
	global_load_lds_dwordx4 v[220:221], off
	s_mov_b32 m0, s61
	s_nop 0
	global_load_lds_dwordx4 v[218:219], off
	s_waitcnt vmcnt(8)
	s_waitcnt lgkmcnt(0)
	s_barrier
	v_mfma_f32_16x16x32_bf16 v[128:131], v[148:151], v[186:189], v[128:131]
	v_mfma_f32_16x16x32_bf16 v[128:131], v[152:155], v[194:197], v[128:131]
	v_mfma_f32_16x16x32_bf16 v[124:127], v[162:165], v[194:197], v[124:127]
	v_mfma_f32_16x16x32_bf16 v[124:127], v[158:161], v[186:189], v[124:127]
	v_mfma_f32_16x16x32_bf16 v[120:123], v[170:173], v[186:189], v[120:123]
	v_mfma_f32_16x16x32_bf16 v[120:123], v[174:177], v[194:197], v[120:123]
	v_mfma_f32_16x16x32_bf16 v[116:119], v[182:185], v[194:197], v[116:119]
	v_mfma_f32_16x16x32_bf16 v[116:119], v[178:181], v[186:189], v[116:119]
	v_mfma_f32_16x16x32_bf16 v[100:103], v[178:181], v[190:193], v[100:103]
	v_mfma_f32_16x16x32_bf16 v[100:103], v[182:185], v[198:201], v[100:103]
	v_mfma_f32_16x16x32_bf16 v[104:107], v[174:177], v[198:201], v[104:107]
	v_mfma_f32_16x16x32_bf16 v[104:107], v[170:173], v[190:193], v[104:107]
	v_mfma_f32_16x16x32_bf16 v[108:111], v[158:161], v[190:193], v[108:111]
	v_mfma_f32_16x16x32_bf16 v[108:111], v[162:165], v[198:201], v[108:111]
	v_mfma_f32_16x16x32_bf16 v[112:115], v[152:155], v[198:201], v[112:115]
	v_mfma_f32_16x16x32_bf16 v[112:115], v[148:151], v[190:193], v[112:115]
	v_mfma_f32_16x16x32_bf16 v[96:99], v[148:151], v[202:205], v[96:99]
	v_mfma_f32_16x16x32_bf16 v[96:99], v[152:155], v[210:213], v[96:99]
	v_mfma_f32_16x16x32_bf16 v[92:95], v[162:165], v[210:213], v[92:95]
	v_mfma_f32_16x16x32_bf16 v[92:95], v[158:161], v[202:205], v[92:95]
	v_mfma_f32_16x16x32_bf16 v[88:91], v[170:173], v[202:205], v[88:91]
	v_mfma_f32_16x16x32_bf16 v[88:91], v[174:177], v[210:213], v[88:91]
	v_mfma_f32_16x16x32_bf16 v[84:87], v[182:185], v[210:213], v[84:87]
	v_mfma_f32_16x16x32_bf16 v[84:87], v[178:181], v[202:205], v[84:87]
	v_mfma_f32_16x16x32_bf16 v[68:71], v[178:181], v[206:209], v[68:71]
	v_mfma_f32_16x16x32_bf16 v[68:71], v[182:185], v[214:217], v[68:71]
	v_mfma_f32_16x16x32_bf16 v[72:75], v[174:177], v[214:217], v[72:75]
	v_mfma_f32_16x16x32_bf16 v[72:75], v[170:173], v[206:209], v[72:75]
	v_mfma_f32_16x16x32_bf16 v[76:79], v[158:161], v[206:209], v[76:79]
	v_mfma_f32_16x16x32_bf16 v[76:79], v[162:165], v[214:217], v[76:79]
	v_mfma_f32_16x16x32_bf16 v[80:83], v[152:155], v[214:217], v[80:83]
	v_mfma_f32_16x16x32_bf16 v[80:83], v[148:151], v[206:209], v[80:83]
	s_barrier
	s_add_i32 s58, s70, s34
	v_lshl_add_u64 v[218:219], v[166:167], 0, s[24:25]
	s_mov_b32 m0, s58
	ds_read_b128 v[186:189], v145 offset:49152
	ds_read_b128 v[190:193], v145 offset:51200
	ds_read_b128 v[194:197], v146 offset:49152
	ds_read_b128 v[198:201], v146 offset:51200
	ds_read_b128 v[202:205], v145 offset:53248
	ds_read_b128 v[206:209], v145 offset:55296
	ds_read_b128 v[210:213], v146 offset:53248
	ds_read_b128 v[214:217], v146 offset:55296
	global_load_lds_dwordx4 v[218:219], off
	v_lshl_add_u64 v[218:219], v[166:167], 0, s[28:29]
	s_add_i32 m0, s58, 0x2000
	s_add_i32 s58, s71, s34
	global_load_lds_dwordx4 v[218:219], off
	v_lshl_add_u64 v[218:219], v[166:167], 0, s[36:37]
	s_mov_b32 m0, s58
	v_lshl_add_u64 v[166:167], v[166:167], 0, s[40:41]
	global_load_lds_dwordx4 v[218:219], off
	s_add_i32 m0, s58, 0x2000
	s_nop 0
	global_load_lds_dwordx4 v[166:167], off
	s_waitcnt vmcnt(4)
	s_waitcnt lgkmcnt(0)
	s_barrier
	v_mfma_f32_16x16x32_bf16 v[64:67], v[148:151], v[186:189], v[64:67]
	v_mfma_f32_16x16x32_bf16 v[64:67], v[152:155], v[194:197], v[64:67]
	v_mfma_f32_16x16x32_bf16 v[60:63], v[162:165], v[194:197], v[60:63]
	v_mfma_f32_16x16x32_bf16 v[60:63], v[158:161], v[186:189], v[60:63]
	v_mfma_f32_16x16x32_bf16 v[56:59], v[170:173], v[186:189], v[56:59]
	v_mfma_f32_16x16x32_bf16 v[56:59], v[174:177], v[194:197], v[56:59]
	v_mfma_f32_16x16x32_bf16 v[52:55], v[182:185], v[194:197], v[52:55]
	v_mfma_f32_16x16x32_bf16 v[52:55], v[178:181], v[186:189], v[52:55]
	v_mfma_f32_16x16x32_bf16 v[36:39], v[178:181], v[190:193], v[36:39]
	v_mfma_f32_16x16x32_bf16 v[36:39], v[182:185], v[198:201], v[36:39]
	v_mfma_f32_16x16x32_bf16 v[40:43], v[174:177], v[198:201], v[40:43]
	v_mfma_f32_16x16x32_bf16 v[40:43], v[170:173], v[190:193], v[40:43]
	v_mfma_f32_16x16x32_bf16 v[44:47], v[158:161], v[190:193], v[44:47]
	v_mfma_f32_16x16x32_bf16 v[44:47], v[162:165], v[198:201], v[44:47]
	v_mfma_f32_16x16x32_bf16 v[48:51], v[152:155], v[198:201], v[48:51]
	v_mfma_f32_16x16x32_bf16 v[48:51], v[148:151], v[190:193], v[48:51]
	v_mfma_f32_16x16x32_bf16 v[32:35], v[148:151], v[202:205], v[32:35]
	v_mfma_f32_16x16x32_bf16 v[32:35], v[152:155], v[210:213], v[32:35]
	v_mfma_f32_16x16x32_bf16 v[28:31], v[162:165], v[210:213], v[28:31]
	v_mfma_f32_16x16x32_bf16 v[28:31], v[158:161], v[202:205], v[28:31]
	v_mfma_f32_16x16x32_bf16 v[24:27], v[170:173], v[202:205], v[24:27]
	v_mfma_f32_16x16x32_bf16 v[24:27], v[174:177], v[210:213], v[24:27]
	v_mfma_f32_16x16x32_bf16 v[20:23], v[182:185], v[210:213], v[20:23]
	v_mfma_f32_16x16x32_bf16 v[20:23], v[178:181], v[202:205], v[20:23]
	v_mfma_f32_16x16x32_bf16 v[4:7], v[178:181], v[206:209], v[4:7]
	v_mfma_f32_16x16x32_bf16 v[4:7], v[182:185], v[214:217], v[4:7]
	v_mfma_f32_16x16x32_bf16 v[8:11], v[174:177], v[214:217], v[8:11]
	v_mfma_f32_16x16x32_bf16 v[8:11], v[170:173], v[206:209], v[8:11]
	v_mfma_f32_16x16x32_bf16 v[12:15], v[158:161], v[206:209], v[12:15]
	v_mfma_f32_16x16x32_bf16 v[12:15], v[162:165], v[214:217], v[12:15]
	v_mfma_f32_16x16x32_bf16 v[16:19], v[152:155], v[214:217], v[16:19]
	v_mfma_f32_16x16x32_bf16 v[16:19], v[148:151], v[206:209], v[16:19]
	s_barrier
	s_add_i32 s77, s77, 2
	s_add_u32 s56, s56, 0x100
	s_addc_u32 s57, s57, 0
	s_cmp_gt_u32 s77, 61
	s_cbranch_scc0 .LBB0_1371
	s_add_u32 s56, s53, 0xffffff00
	s_addc_u32 s57, s72, -1
	s_andn2_b64 vcc, exec, s[6:7]
	s_cbranch_vccnz .LBB0_1362
	v_mov_b32_e32 v4, 0
	s_mov_b32 s0, s48
	s_mov_b32 s8, s50
	s_mov_b64 s[18:19], s[54:55]
	s_mov_b32 s63, s52
	v_mov_b32_e32 v5, v4
	v_mov_b32_e32 v6, v4
	v_mov_b32_e32 v7, v4
	v_mov_b32_e32 v8, v4
	v_mov_b32_e32 v9, v4
	v_mov_b32_e32 v10, v4
	v_mov_b32_e32 v11, v4
	v_mov_b32_e32 v20, v4
	v_mov_b32_e32 v21, v4
	v_mov_b32_e32 v22, v4
	v_mov_b32_e32 v23, v4
	v_mov_b32_e32 v24, v4
	v_mov_b32_e32 v25, v4
	v_mov_b32_e32 v26, v4
	v_mov_b32_e32 v27, v4
	v_mov_b32_e32 v36, v4
	v_mov_b32_e32 v37, v4
	v_mov_b32_e32 v38, v4
	v_mov_b32_e32 v39, v4
	v_mov_b32_e32 v40, v4
	v_mov_b32_e32 v41, v4
	v_mov_b32_e32 v42, v4
	v_mov_b32_e32 v43, v4
	v_mov_b32_e32 v52, v4
	v_mov_b32_e32 v53, v4
	v_mov_b32_e32 v54, v4
	v_mov_b32_e32 v55, v4
	v_mov_b32_e32 v56, v4
	v_mov_b32_e32 v57, v4
	v_mov_b32_e32 v58, v4
	v_mov_b32_e32 v59, v4
	v_mov_b32_e32 v12, v4
	v_mov_b32_e32 v13, v4
	v_mov_b32_e32 v14, v4
	v_mov_b32_e32 v15, v4
	v_mov_b32_e32 v16, v4
	v_mov_b32_e32 v17, v4
	v_mov_b32_e32 v18, v4
	v_mov_b32_e32 v19, v4
	v_mov_b32_e32 v28, v4
	v_mov_b32_e32 v29, v4
	v_mov_b32_e32 v30, v4
	v_mov_b32_e32 v31, v4
	v_mov_b32_e32 v32, v4
	v_mov_b32_e32 v33, v4
	v_mov_b32_e32 v34, v4
	v_mov_b32_e32 v35, v4
	v_mov_b32_e32 v44, v4
	v_mov_b32_e32 v45, v4
	v_mov_b32_e32 v46, v4
	v_mov_b32_e32 v47, v4
	v_mov_b32_e32 v48, v4
	v_mov_b32_e32 v49, v4
	v_mov_b32_e32 v50, v4
	v_mov_b32_e32 v51, v4
	v_mov_b32_e32 v60, v4
	v_mov_b32_e32 v61, v4
	v_mov_b32_e32 v62, v4
	v_mov_b32_e32 v63, v4
	v_mov_b32_e32 v64, v4
	v_mov_b32_e32 v65, v4
	v_mov_b32_e32 v66, v4
	v_mov_b32_e32 v67, v4
	v_mov_b32_e32 v68, v4
	v_mov_b32_e32 v69, v4
	v_mov_b32_e32 v70, v4
	v_mov_b32_e32 v71, v4
	v_mov_b32_e32 v72, v4
	v_mov_b32_e32 v73, v4
	v_mov_b32_e32 v74, v4
	v_mov_b32_e32 v75, v4
	v_mov_b32_e32 v84, v4
	v_mov_b32_e32 v85, v4
	v_mov_b32_e32 v86, v4
	v_mov_b32_e32 v87, v4
	v_mov_b32_e32 v88, v4
	v_mov_b32_e32 v89, v4
	v_mov_b32_e32 v90, v4
	v_mov_b32_e32 v91, v4
	v_mov_b32_e32 v100, v4
	v_mov_b32_e32 v101, v4
	v_mov_b32_e32 v102, v4
	v_mov_b32_e32 v103, v4
	v_mov_b32_e32 v104, v4
	v_mov_b32_e32 v105, v4
	v_mov_b32_e32 v106, v4
	v_mov_b32_e32 v107, v4
	v_mov_b32_e32 v116, v4
	v_mov_b32_e32 v117, v4
	v_mov_b32_e32 v118, v4
	v_mov_b32_e32 v119, v4
	v_mov_b32_e32 v120, v4
	v_mov_b32_e32 v121, v4
	v_mov_b32_e32 v122, v4
	v_mov_b32_e32 v123, v4
	v_mov_b32_e32 v76, v4
	v_mov_b32_e32 v77, v4
	v_mov_b32_e32 v78, v4
	v_mov_b32_e32 v79, v4
	v_mov_b32_e32 v80, v4
	v_mov_b32_e32 v81, v4
	v_mov_b32_e32 v82, v4
	v_mov_b32_e32 v83, v4
	v_mov_b32_e32 v92, v4
	v_mov_b32_e32 v93, v4
	v_mov_b32_e32 v94, v4
	v_mov_b32_e32 v95, v4
	v_mov_b32_e32 v96, v4
	v_mov_b32_e32 v97, v4
	v_mov_b32_e32 v98, v4
	v_mov_b32_e32 v99, v4
	v_mov_b32_e32 v108, v4
	v_mov_b32_e32 v109, v4
	v_mov_b32_e32 v110, v4
	v_mov_b32_e32 v111, v4
	v_mov_b32_e32 v112, v4
	v_mov_b32_e32 v113, v4
	v_mov_b32_e32 v114, v4
	v_mov_b32_e32 v115, v4
	v_mov_b32_e32 v124, v4
	v_mov_b32_e32 v125, v4
	v_mov_b32_e32 v126, v4
	v_mov_b32_e32 v127, v4
	v_mov_b32_e32 v128, v4
	v_mov_b32_e32 v129, v4
	v_mov_b32_e32 v130, v4
	v_mov_b32_e32 v131, v4
	s_andn2_b64 vcc, exec, s[4:5]
	s_cbranch_vccnz .LBB0_1363
